# adds: route q-GEMM LDS fragment reads software-pipelined (6 rotating buffers, constants rematerialised), scan recurrence hazard-nop cleanup, LayerNorm(mid) parameter loads batched
# speedup vs baseline: 1.0375x; 1.0199x over previous
.LBB0_620:
	v_mfma_f32_32x32x16_bf16 v[0:15], v[48:51], v[110:113], 0
	v_add_u32_e32 v116, 0x400, v144
	v_add_u32_e32 v117, 0x1000, v144
	v_add_u32_e32 v151, 0x1400, v144
	v_mfma_f32_32x32x16_bf16 v[32:47], v[48:51], v[106:109], 0
	s_nop 11
	ds_write2_b32 v144, v8, v40 offset1:32
	ds_write2_b32 v144, v9, v41 offset0:128 offset1:160
	ds_write2_b32 v116, v10, v42 offset1:32
	v_mfma_f32_32x32x16_bf16 v[16:31], v[48:51], v[102:105], 0
	ds_write2_b32 v116, v11, v43 offset0:128 offset1:160
	ds_write2_b32 v117, v12, v44 offset1:32
	ds_write2_b32 v117, v13, v45 offset0:128 offset1:160
	ds_write2_b32 v151, v14, v46 offset1:32
	ds_write2_b32 v151, v15, v47 offset0:128 offset1:160
	v_mfma_f32_32x32x16_bf16 v[40:55], v[48:51], v[94:97], 0
	s_nop 11
	ds_write2_b32 v144, v24, v48 offset0:64 offset1:96
	ds_write2_b32 v144, v25, v49 offset0:192 offset1:224
	ds_write2_b32 v116, v26, v50 offset0:64 offset1:96
	ds_write2_b32 v116, v27, v51 offset0:192 offset1:224
	ds_write2_b32 v117, v28, v52 offset0:64 offset1:96
	ds_write2_b32 v117, v29, v53 offset0:192 offset1:224
	ds_write2_b32 v151, v30, v54 offset0:64 offset1:96
	ds_write2_b32 v151, v31, v55 offset0:192 offset1:224
	ds_read2st64_b64 v[12:15], v148 offset0:14 offset1:15
	ds_read2st64_b64 v[24:27], v148 offset0:12 offset1:13
	ds_read2st64_b64 v[28:31], v148 offset0:10 offset1:11
	ds_read2st64_b64 v[48:51], v148 offset0:8 offset1:9
	ds_read2st64_b64 v[52:55], v148 offset0:6 offset1:7
	ds_read2st64_b64 v[152:155], v148 offset0:4 offset1:5
	ds_read2st64_b64 v[156:159], v148 offset0:2 offset1:3
	ds_read2st64_b64 v[8:11], v148 offset1:1
	s_waitcnt lgkmcnt(7)
	v_fma_f32 v14, -v131, v115, v14
	v_fma_f32 v15, v131, v114, v15
	v_fmac_f32_e32 v14, v150, v114
	v_fmac_f32_e32 v15, v150, v115
	v_fma_f32 v12, -v131, v15, v12
	v_fmac_f32_e32 v13, v131, v14
	v_cvt_pk_bf16_f32 v114, v14, v15
	v_fmac_f32_e32 v12, v150, v14
	v_fmac_f32_e32 v13, v150, v15
	ds_write_b32 v149, v114 offset:16624
	v_cvt_pk_bf16_f32 v14, v12, v13
	ds_write_b32 v149, v14 offset:16352
	s_waitcnt lgkmcnt(8)
	v_fma_f32 v14, -v131, v13, v26
	v_fmac_f32_e32 v14, v150, v12
	v_fma_f32 v12, v131, v12, v27
	v_fmac_f32_e32 v12, v150, v13
	v_cvt_pk_bf16_f32 v13, v14, v12
	ds_write_b32 v149, v13 offset:16080
	v_fma_f32 v13, -v131, v12, v24
	v_fmac_f32_e32 v25, v131, v14
	v_fmac_f32_e32 v13, v150, v14
	v_fmac_f32_e32 v25, v150, v12
	v_cvt_pk_bf16_f32 v12, v13, v25
	ds_write_b32 v149, v12 offset:15808
	s_waitcnt lgkmcnt(9)
	v_fma_f32 v12, -v131, v25, v30
	v_fmac_f32_e32 v12, v150, v13
	v_fma_f32 v13, v131, v13, v31
	v_fmac_f32_e32 v13, v150, v25
	v_cvt_pk_bf16_f32 v14, v12, v13
	ds_write_b32 v149, v14 offset:15536
	v_fma_f32 v14, -v131, v13, v28
	v_fmac_f32_e32 v29, v131, v12
	v_fmac_f32_e32 v14, v150, v12
	v_fmac_f32_e32 v29, v150, v13
	v_cvt_pk_bf16_f32 v12, v14, v29
	ds_write_b32 v149, v12 offset:15264
	s_waitcnt lgkmcnt(10)
	v_fma_f32 v12, -v131, v29, v50
	v_fma_f32 v13, v131, v14, v51
	v_fmac_f32_e32 v12, v150, v14
	v_fmac_f32_e32 v13, v150, v29
	v_cvt_pk_bf16_f32 v14, v12, v13
	ds_write_b32 v149, v14 offset:14992
	v_fma_f32 v14, -v131, v13, v48
	v_fmac_f32_e32 v49, v131, v12
	v_fmac_f32_e32 v14, v150, v12
	v_fmac_f32_e32 v49, v150, v13
	v_cvt_pk_bf16_f32 v12, v14, v49
	ds_write_b32 v149, v12 offset:14720
	s_waitcnt lgkmcnt(11)
	v_fma_f32 v12, -v131, v49, v54
	v_fma_f32 v13, v131, v14, v55
	v_fmac_f32_e32 v12, v150, v14
	v_fmac_f32_e32 v13, v150, v49
	v_cvt_pk_bf16_f32 v14, v12, v13
	ds_write_b32 v149, v14 offset:14448
	v_fma_f32 v14, -v131, v13, v52
	v_fmac_f32_e32 v53, v131, v12
	v_fmac_f32_e32 v14, v150, v12
	v_fmac_f32_e32 v53, v150, v13
	v_cvt_pk_bf16_f32 v12, v14, v53
	ds_write_b32 v149, v12 offset:14176
	s_waitcnt lgkmcnt(12)
	v_fma_f32 v12, -v131, v53, v154
	v_fma_f32 v13, v131, v14, v155
	v_fmac_f32_e32 v12, v150, v14
	v_fmac_f32_e32 v13, v150, v53
	v_cvt_pk_bf16_f32 v14, v12, v13
	ds_write_b32 v149, v14 offset:13904
	v_fma_f32 v14, -v131, v13, v152
	v_fmac_f32_e32 v153, v131, v12
	v_fmac_f32_e32 v14, v150, v12
	v_fmac_f32_e32 v153, v150, v13
	v_cvt_pk_bf16_f32 v12, v14, v153
	ds_write_b32 v149, v12 offset:13632
	s_waitcnt lgkmcnt(13)
	v_fma_f32 v12, -v131, v153, v158
	v_fma_f32 v13, v131, v14, v159
	v_fmac_f32_e32 v12, v150, v14
	v_fmac_f32_e32 v13, v150, v153
	v_cvt_pk_bf16_f32 v14, v12, v13
	ds_write_b32 v149, v14 offset:13360
	v_fma_f32 v14, -v131, v13, v156
	v_fmac_f32_e32 v157, v131, v12
	v_fmac_f32_e32 v14, v150, v12
	v_fmac_f32_e32 v157, v150, v13
	s_waitcnt lgkmcnt(13)
	v_fma_f32 v10, -v131, v157, v10
	v_fma_f32 v11, v131, v14, v11
	v_cvt_pk_bf16_f32 v12, v14, v157
	v_fmac_f32_e32 v10, v150, v14
	v_fmac_f32_e32 v11, v150, v157
	ds_write_b32 v149, v12 offset:13088
	v_fma_f32 v8, -v131, v11, v8
	v_fmac_f32_e32 v9, v131, v10
	v_cvt_pk_bf16_f32 v12, v10, v11
	v_fmac_f32_e32 v8, v150, v10
	v_fmac_f32_e32 v9, v150, v11
	ds_write_b32 v149, v12 offset:12816
	v_cvt_pk_bf16_f32 v10, v8, v9
	ds_write_b32 v149, v10 offset:12544
	ds_write2_b32 v144, v0, v32 offset1:32
	ds_write2_b32 v144, v1, v33 offset0:128 offset1:160
	ds_write2_b32 v116, v2, v34 offset1:32
	ds_write2_b32 v116, v3, v35 offset0:128 offset1:160
	ds_write2_b32 v117, v4, v36 offset1:32
	ds_write2_b32 v117, v5, v37 offset0:128 offset1:160
	ds_write2_b32 v151, v6, v38 offset1:32
	ds_write2_b32 v151, v7, v39 offset0:128 offset1:160
	ds_write2_b32 v144, v16, v40 offset0:64 offset1:96
	ds_write2_b32 v144, v17, v41 offset0:192 offset1:224
	ds_write2_b32 v116, v18, v42 offset0:64 offset1:96
	ds_write2_b32 v116, v19, v43 offset0:192 offset1:224
	ds_write2_b32 v117, v20, v44 offset0:64 offset1:96
	ds_write2_b32 v117, v21, v45 offset0:192 offset1:224
	ds_write2_b32 v151, v22, v46 offset0:64 offset1:96
	ds_write2_b32 v151, v23, v47 offset0:192 offset1:224
	ds_read2st64_b64 v[0:3], v148 offset0:14 offset1:15
	ds_read2st64_b64 v[4:7], v148 offset0:12 offset1:13
	ds_read2st64_b64 v[10:13], v148 offset0:10 offset1:11
	ds_read2st64_b64 v[14:17], v148 offset0:8 offset1:9
	ds_read2st64_b64 v[18:21], v148 offset0:6 offset1:7
	ds_read2st64_b64 v[22:25], v148 offset0:4 offset1:5
	ds_read2st64_b64 v[26:29], v148 offset0:2 offset1:3
	ds_read2st64_b64 v[114:117], v148 offset1:1
	s_waitcnt lgkmcnt(7)
	v_fma_f32 v2, -v131, v9, v2
	v_fma_f32 v3, v131, v8, v3
	v_fmac_f32_e32 v2, v150, v8
	v_fmac_f32_e32 v3, v150, v9
	v_fma_f32 v0, -v131, v3, v0
	v_fmac_f32_e32 v1, v131, v2
	v_cvt_pk_bf16_f32 v8, v2, v3
	v_fmac_f32_e32 v0, v150, v2
	v_fmac_f32_e32 v1, v150, v3
	ds_write_b32 v149, v8 offset:12272
	v_cvt_pk_bf16_f32 v2, v0, v1
	ds_write_b32 v149, v2 offset:12000
	s_waitcnt lgkmcnt(8)
	v_fma_f32 v2, -v131, v1, v6
	v_fmac_f32_e32 v2, v150, v0
	v_fma_f32 v0, v131, v0, v7
	v_fmac_f32_e32 v0, v150, v1
	v_cvt_pk_bf16_f32 v1, v2, v0
	ds_write_b32 v149, v1 offset:11728
	v_fma_f32 v1, -v131, v0, v4
	v_fmac_f32_e32 v5, v131, v2
	v_fmac_f32_e32 v1, v150, v2
	v_fmac_f32_e32 v5, v150, v0
	v_cvt_pk_bf16_f32 v0, v1, v5
	ds_write_b32 v149, v0 offset:11456
	s_waitcnt lgkmcnt(9)
	v_fma_f32 v0, -v131, v5, v12
	v_fmac_f32_e32 v0, v150, v1
	v_fma_f32 v1, v131, v1, v13
	v_fmac_f32_e32 v1, v150, v5
	v_cvt_pk_bf16_f32 v2, v0, v1
	ds_write_b32 v149, v2 offset:11184
	v_fma_f32 v2, -v131, v1, v10
	v_fmac_f32_e32 v11, v131, v0
	v_fmac_f32_e32 v2, v150, v0
	v_fmac_f32_e32 v11, v150, v1
	v_cvt_pk_bf16_f32 v0, v2, v11
	ds_write_b32 v149, v0 offset:10912
	s_waitcnt lgkmcnt(10)
	v_fma_f32 v0, -v131, v11, v16
	v_fma_f32 v1, v131, v2, v17
	v_fmac_f32_e32 v0, v150, v2
	v_fmac_f32_e32 v1, v150, v11
	v_cvt_pk_bf16_f32 v2, v0, v1
	ds_write_b32 v149, v2 offset:10640
	v_fma_f32 v2, -v131, v1, v14
	v_fmac_f32_e32 v15, v131, v0
	v_fmac_f32_e32 v2, v150, v0
	v_fmac_f32_e32 v15, v150, v1
	v_cvt_pk_bf16_f32 v0, v2, v15
	ds_write_b32 v149, v0 offset:10368
	s_waitcnt lgkmcnt(11)
	v_fma_f32 v0, -v131, v15, v20
	v_fma_f32 v1, v131, v2, v21
	v_fmac_f32_e32 v0, v150, v2
	v_fmac_f32_e32 v1, v150, v15
	v_cvt_pk_bf16_f32 v2, v0, v1
	ds_write_b32 v149, v2 offset:10096
	v_fma_f32 v2, -v131, v1, v18
	v_fmac_f32_e32 v19, v131, v0
	v_fmac_f32_e32 v2, v150, v0
	v_fmac_f32_e32 v19, v150, v1
	v_cvt_pk_bf16_f32 v0, v2, v19
	ds_write_b32 v149, v0 offset:9824
	s_waitcnt lgkmcnt(12)
	v_fma_f32 v0, -v131, v19, v24
	v_fma_f32 v1, v131, v2, v25
	v_fmac_f32_e32 v0, v150, v2
	v_fmac_f32_e32 v1, v150, v19
	v_cvt_pk_bf16_f32 v2, v0, v1
	ds_write_b32 v149, v2 offset:9552
	v_fma_f32 v2, -v131, v1, v22
	v_fmac_f32_e32 v23, v131, v0
	v_fmac_f32_e32 v2, v150, v0
	v_fmac_f32_e32 v23, v150, v1
	v_cvt_pk_bf16_f32 v0, v2, v23
	ds_write_b32 v149, v0 offset:9280
	s_waitcnt lgkmcnt(13)
	v_fma_f32 v0, -v131, v23, v28
	v_fma_f32 v1, v131, v2, v29
	v_fmac_f32_e32 v0, v150, v2
	v_fmac_f32_e32 v1, v150, v23
	v_cvt_pk_bf16_f32 v2, v0, v1
	ds_write_b32 v149, v2 offset:9008
	v_fma_f32 v2, -v131, v1, v26
	v_fmac_f32_e32 v27, v131, v0
	v_fmac_f32_e32 v2, v150, v0
	v_fmac_f32_e32 v27, v150, v1
	v_cvt_pk_bf16_f32 v0, v2, v27
	ds_write_b32 v149, v0 offset:8736
	s_waitcnt lgkmcnt(14)
	v_fma_f32 v0, -v131, v27, v116
	v_fma_f32 v1, v131, v2, v117
	v_fmac_f32_e32 v0, v150, v2
	v_fmac_f32_e32 v1, v150, v27
	v_fma_f32 v114, -v131, v1, v114
	v_fmac_f32_e32 v115, v131, v0
	v_cvt_pk_bf16_f32 v2, v0, v1
	v_fmac_f32_e32 v114, v150, v0
	v_fmac_f32_e32 v115, v150, v1
	ds_write_b32 v149, v2 offset:8464
	v_cvt_pk_bf16_f32 v0, v114, v115
	ds_write_b32 v149, v0 offset:8192
	ds_read_b128 v[0:3], v128 offset:8192
	ds_read_b128 v[16:19], v128 offset:8224
	s_waitcnt lgkmcnt(1)
	v_mfma_f32_32x32x16_bf16 v[0:15], v[0:3], v[90:93], 0
	ds_read_b128 v[32:35], v128 offset:8256
	ds_read_b128 v[36:39], v128 offset:8288
	s_waitcnt lgkmcnt(2)
	v_mfma_f32_32x32x16_bf16 v[16:31], v[16:19], v[86:89], 0
	s_waitcnt lgkmcnt(1)
	v_mfma_f32_32x32x16_bf16 v[0:15], v[32:35], v[82:85], v[0:15]
	s_waitcnt lgkmcnt(0)
	v_mfma_f32_32x32x16_bf16 v[16:31], v[36:39], v[78:81], v[16:31]
	ds_read_b128 v[32:35], v128 offset:8320
	ds_read_b128 v[36:39], v128 offset:8352
	s_waitcnt lgkmcnt(1)
	v_mfma_f32_32x32x16_bf16 v[0:15], v[32:35], v[74:77], v[0:15]
	s_waitcnt lgkmcnt(0)
	v_mfma_f32_32x32x16_bf16 v[16:31], v[36:39], v[70:73], v[16:31]
	ds_read_b128 v[32:35], v128 offset:8384
	ds_read_b128 v[36:39], v128 offset:8416
	s_waitcnt lgkmcnt(1)
	v_mfma_f32_32x32x16_bf16 v[0:15], v[32:35], v[66:69], v[0:15]
	s_waitcnt lgkmcnt(0)
	v_mfma_f32_32x32x16_bf16 v[16:31], v[36:39], v[62:65], v[16:31]
	s_and_saveexec_b64 s[48:49], vcc
	s_cbranch_execz .LBB0_617
	s_nop 9
	v_add_f32_e32 v0, v0, v16
	v_cvt_pk_bf16_f32 v0, v0, s0
	ds_write_b16 v145, v0
	v_add_f32_e32 v0, v1, v17
	v_cvt_pk_bf16_f32 v0, v0, s0
	ds_write_b16 v145, v0 offset:32
	v_add_f32_e32 v0, v2, v18
	v_cvt_pk_bf16_f32 v0, v0, s0
	ds_write_b16 v145, v0 offset:64
	v_add_f32_e32 v0, v3, v19
	v_cvt_pk_bf16_f32 v0, v0, s0
	ds_write_b16 v145, v0 offset:96
	v_add_f32_e32 v0, v4, v20
	v_cvt_pk_bf16_f32 v0, v0, s0
	ds_write_b16 v145, v0 offset:256
	v_add_f32_e32 v0, v5, v21
	v_cvt_pk_bf16_f32 v0, v0, s0
	ds_write_b16 v145, v0 offset:288
	v_add_f32_e32 v0, v6, v22
	v_cvt_pk_bf16_f32 v0, v0, s0
	ds_write_b16 v145, v0 offset:320
	v_add_f32_e32 v0, v7, v23
	v_cvt_pk_bf16_f32 v0, v0, s0
	ds_write_b16 v145, v0 offset:352
	v_add_f32_e32 v0, v8, v24
	v_cvt_pk_bf16_f32 v0, v0, s0
	ds_write_b16 v145, v0 offset:512
	v_add_f32_e32 v0, v9, v25
	v_cvt_pk_bf16_f32 v0, v0, s0
	ds_write_b16 v145, v0 offset:544
	v_add_f32_e32 v0, v10, v26
	v_cvt_pk_bf16_f32 v0, v0, s0
	ds_write_b16 v145, v0 offset:576
	v_add_f32_e32 v0, v11, v27
	v_cvt_pk_bf16_f32 v0, v0, s0
	ds_write_b16 v145, v0 offset:608
	v_add_f32_e32 v0, v12, v28
	v_cvt_pk_bf16_f32 v0, v0, s0
	ds_write_b16 v145, v0 offset:768
	v_add_f32_e32 v0, v13, v29
	v_cvt_pk_bf16_f32 v0, v0, s0
	ds_write_b16 v145, v0 offset:800
	v_add_f32_e32 v0, v14, v30
	v_cvt_pk_bf16_f32 v0, v0, s0
	ds_write_b16 v145, v0 offset:832
	v_add_f32_e32 v0, v15, v31
	v_cvt_pk_bf16_f32 v0, v0, s0
	ds_write_b16 v145, v0 offset:864
	s_branch .LBB0_617

.LBB0_627:
	v_mfma_f32_32x32x16_bf16 v[0:15], v[46:49], v[110:113], 0
	v_add_u32_e32 v98, 0x400, v152
	v_add_u32_e32 v99, 0x1000, v152
	v_add_u32_e32 v100, 0x1400, v152
	v_mfma_f32_32x32x16_bf16 v[30:45], v[46:49], v[106:109], 0
	s_nop 11
	ds_write2_b32 v152, v0, v30 offset1:32
	ds_write2_b32 v152, v1, v31 offset0:128 offset1:160
	v_mfma_f32_32x32x16_bf16 v[16:31], v[46:49], v[102:105], 0
	ds_write2_b32 v98, v2, v32 offset1:32
	ds_write2_b32 v98, v3, v33 offset0:128 offset1:160
	ds_write2_b32 v99, v4, v34 offset1:32
	ds_write2_b32 v99, v5, v35 offset0:128 offset1:160
	ds_write2_b32 v100, v6, v36 offset1:32
	ds_write2_b32 v100, v7, v37 offset0:128 offset1:160
	v_mfma_f32_32x32x16_bf16 v[46:61], v[46:49], v[94:97], 0
	s_nop 11
	ds_write2_b32 v152, v16, v46 offset0:64 offset1:96
	ds_write2_b32 v152, v17, v47 offset0:192 offset1:224
	ds_write2_b32 v98, v18, v48 offset0:64 offset1:96
	ds_write2_b32 v98, v19, v49 offset0:192 offset1:224
	ds_write2_b32 v99, v20, v50 offset0:64 offset1:96
	ds_write2_b32 v99, v21, v51 offset0:192 offset1:224
	ds_write2_b32 v100, v22, v52 offset0:64 offset1:96
	ds_write2_b32 v100, v23, v53 offset0:192 offset1:224
	ds_read2st64_b64 v[4:7], v154 offset1:1
	ds_read2st64_b64 v[16:19], v154 offset0:2 offset1:3
	ds_read2st64_b64 v[20:23], v154 offset0:4 offset1:5
	ds_read2st64_b64 v[32:35], v154 offset0:6 offset1:7
	ds_read2st64_b64 v[46:49], v154 offset0:8 offset1:9
	ds_read2st64_b64 v[50:53], v154 offset0:10 offset1:11
	ds_read2st64_b64 v[156:159], v154 offset0:12 offset1:13
	ds_read2st64_b64 v[0:3], v154 offset0:14 offset1:15
	s_waitcnt lgkmcnt(7)
	v_fma_f32 v4, -v131, v101, v4
	v_fma_f32 v5, v131, v135, v5
	v_fmac_f32_e32 v4, v150, v135
	v_fmac_f32_e32 v5, v150, v101
	v_fma_f32 v6, -v131, v5, v6
	v_fmac_f32_e32 v7, v131, v4
	v_cvt_pk_bf16_f32 v36, v4, v5
	v_fmac_f32_e32 v6, v150, v4
	v_fmac_f32_e32 v7, v150, v5
	ds_write_b32 v155, v36 offset:8192
	v_cvt_pk_bf16_f32 v4, v6, v7
	ds_write_b32 v155, v4 offset:8464
	s_waitcnt lgkmcnt(8)
	v_fma_f32 v4, -v131, v7, v16
	v_fma_f32 v5, v131, v6, v17
	v_fmac_f32_e32 v4, v150, v6
	v_fmac_f32_e32 v5, v150, v7
	v_cvt_pk_bf16_f32 v6, v4, v5
	ds_write_b32 v155, v6 offset:8736
	v_fma_f32 v6, -v131, v5, v18
	v_fmac_f32_e32 v19, v131, v4
	v_fmac_f32_e32 v6, v150, v4
	v_fmac_f32_e32 v19, v150, v5
	v_cvt_pk_bf16_f32 v4, v6, v19
	ds_write_b32 v155, v4 offset:9008
	s_waitcnt lgkmcnt(9)
	v_fma_f32 v4, -v131, v19, v20
	v_fma_f32 v5, v131, v6, v21
	v_fmac_f32_e32 v4, v150, v6
	v_fmac_f32_e32 v5, v150, v19
	v_cvt_pk_bf16_f32 v6, v4, v5
	ds_write_b32 v155, v6 offset:9280
	v_fma_f32 v6, -v131, v5, v22
	v_fmac_f32_e32 v23, v131, v4
	v_fmac_f32_e32 v6, v150, v4
	v_fmac_f32_e32 v23, v150, v5
	v_cvt_pk_bf16_f32 v4, v6, v23
	ds_write_b32 v155, v4 offset:9552
	s_waitcnt lgkmcnt(10)
	v_fma_f32 v4, -v131, v23, v32
	v_fma_f32 v5, v131, v6, v33
	v_fmac_f32_e32 v4, v150, v6
	v_fmac_f32_e32 v5, v150, v23
	v_cvt_pk_bf16_f32 v6, v4, v5
	ds_write_b32 v155, v6 offset:9824
	v_fma_f32 v6, -v131, v5, v34
	v_fmac_f32_e32 v35, v131, v4
	v_fmac_f32_e32 v6, v150, v4
	v_fmac_f32_e32 v35, v150, v5
	v_cvt_pk_bf16_f32 v4, v6, v35
	ds_write_b32 v155, v4 offset:10096
	s_waitcnt lgkmcnt(11)
	v_fma_f32 v4, -v131, v35, v46
	v_fma_f32 v5, v131, v6, v47
	v_fmac_f32_e32 v4, v150, v6
	v_fmac_f32_e32 v5, v150, v35
	v_cvt_pk_bf16_f32 v6, v4, v5
	ds_write_b32 v155, v6 offset:10368
	v_fma_f32 v6, -v131, v5, v48
	v_fmac_f32_e32 v49, v131, v4
	v_fmac_f32_e32 v6, v150, v4
	v_fmac_f32_e32 v49, v150, v5
	v_cvt_pk_bf16_f32 v4, v6, v49
	ds_write_b32 v155, v4 offset:10640
	s_waitcnt lgkmcnt(12)
	v_fma_f32 v4, -v131, v49, v50
	v_fma_f32 v5, v131, v6, v51
	v_fmac_f32_e32 v4, v150, v6
	v_fmac_f32_e32 v5, v150, v49
	v_cvt_pk_bf16_f32 v6, v4, v5
	ds_write_b32 v155, v6 offset:10912
	v_fma_f32 v6, -v131, v5, v52
	v_fmac_f32_e32 v53, v131, v4
	v_fmac_f32_e32 v6, v150, v4
	v_fmac_f32_e32 v53, v150, v5
	v_cvt_pk_bf16_f32 v4, v6, v53
	ds_write_b32 v155, v4 offset:11184
	s_waitcnt lgkmcnt(13)
	v_fma_f32 v4, -v131, v53, v156
	v_fma_f32 v5, v131, v6, v157
	v_fmac_f32_e32 v4, v150, v6
	v_fmac_f32_e32 v5, v150, v53
	v_cvt_pk_bf16_f32 v6, v4, v5
	ds_write_b32 v155, v6 offset:11456
	v_fma_f32 v6, -v131, v5, v158
	v_fmac_f32_e32 v159, v131, v4
	v_fmac_f32_e32 v6, v150, v4
	v_fmac_f32_e32 v159, v150, v5
	s_waitcnt lgkmcnt(13)
	v_fma_f32 v0, -v131, v159, v0
	v_fma_f32 v1, v131, v6, v1
	v_cvt_pk_bf16_f32 v4, v6, v159
	v_fmac_f32_e32 v0, v150, v6
	v_fmac_f32_e32 v1, v150, v159
	ds_write_b32 v155, v4 offset:11728
	v_fma_f32 v2, -v131, v1, v2
	v_fmac_f32_e32 v3, v131, v0
	v_cvt_pk_bf16_f32 v4, v0, v1
	v_fmac_f32_e32 v2, v150, v0
	v_fmac_f32_e32 v3, v150, v1
	ds_write_b32 v155, v4 offset:12000
	v_cvt_pk_bf16_f32 v0, v2, v3
	ds_write_b32 v155, v0 offset:12272
	ds_write2_b32 v152, v8, v38 offset1:32
	ds_write2_b32 v152, v9, v39 offset0:128 offset1:160
	ds_write2_b32 v98, v10, v40 offset1:32
	ds_write2_b32 v98, v11, v41 offset0:128 offset1:160
	ds_write2_b32 v99, v12, v42 offset1:32
	ds_write2_b32 v99, v13, v43 offset0:128 offset1:160
	ds_write2_b32 v100, v14, v44 offset1:32
	ds_write2_b32 v100, v15, v45 offset0:128 offset1:160
	ds_write2_b32 v152, v24, v54 offset0:64 offset1:96
	ds_write2_b32 v152, v25, v55 offset0:192 offset1:224
	ds_write2_b32 v98, v26, v56 offset0:64 offset1:96
	ds_write2_b32 v98, v27, v57 offset0:192 offset1:224
	ds_write2_b32 v99, v28, v58 offset0:64 offset1:96
	ds_write2_b32 v99, v29, v59 offset0:192 offset1:224
	ds_write2_b32 v100, v30, v60 offset0:64 offset1:96
	ds_write2_b32 v100, v31, v61 offset0:192 offset1:224
	ds_read2st64_b64 v[4:7], v154 offset1:1
	ds_read2st64_b64 v[8:11], v154 offset0:2 offset1:3
	ds_read2st64_b64 v[12:15], v154 offset0:4 offset1:5
	ds_read2st64_b64 v[16:19], v154 offset0:6 offset1:7
	ds_read2st64_b64 v[20:23], v154 offset0:8 offset1:9
	ds_read2st64_b64 v[24:27], v154 offset0:10 offset1:11
	ds_read2st64_b64 v[28:31], v154 offset0:12 offset1:13
	ds_read2st64_b64 v[98:101], v154 offset0:14 offset1:15
	s_waitcnt lgkmcnt(7)
	v_fma_f32 v0, -v131, v3, v4
	v_fma_f32 v1, v131, v2, v5
	v_fmac_f32_e32 v0, v150, v2
	v_fmac_f32_e32 v1, v150, v3
	v_cvt_pk_bf16_f32 v2, v0, v1
	ds_write_b32 v155, v2 offset:12544
	v_fma_f32 v2, -v131, v1, v6
	v_fmac_f32_e32 v7, v131, v0
	v_fmac_f32_e32 v2, v150, v0
	v_fmac_f32_e32 v7, v150, v1
	v_cvt_pk_bf16_f32 v0, v2, v7
	ds_write_b32 v155, v0 offset:12816
	s_waitcnt lgkmcnt(8)
	v_fma_f32 v0, -v131, v7, v8
	v_fma_f32 v1, v131, v2, v9
	v_fmac_f32_e32 v0, v150, v2
	v_fmac_f32_e32 v1, v150, v7
	v_cvt_pk_bf16_f32 v2, v0, v1
	ds_write_b32 v155, v2 offset:13088
	v_fma_f32 v2, -v131, v1, v10
	v_fmac_f32_e32 v11, v131, v0
	v_fmac_f32_e32 v2, v150, v0
	v_fmac_f32_e32 v11, v150, v1
	v_cvt_pk_bf16_f32 v0, v2, v11
	ds_write_b32 v155, v0 offset:13360
	s_waitcnt lgkmcnt(9)
	v_fma_f32 v0, -v131, v11, v12
	v_fma_f32 v1, v131, v2, v13
	v_fmac_f32_e32 v0, v150, v2
	v_fmac_f32_e32 v1, v150, v11
	v_cvt_pk_bf16_f32 v2, v0, v1
	ds_write_b32 v155, v2 offset:13632
	v_fma_f32 v2, -v131, v1, v14
	v_fmac_f32_e32 v15, v131, v0
	v_fmac_f32_e32 v2, v150, v0
	v_fmac_f32_e32 v15, v150, v1
	v_cvt_pk_bf16_f32 v0, v2, v15
	ds_write_b32 v155, v0 offset:13904
	s_waitcnt lgkmcnt(10)
	v_fma_f32 v0, -v131, v15, v16
	v_fma_f32 v1, v131, v2, v17
	v_fmac_f32_e32 v0, v150, v2
	v_fmac_f32_e32 v1, v150, v15
	v_cvt_pk_bf16_f32 v2, v0, v1
	ds_write_b32 v155, v2 offset:14176
	v_fma_f32 v2, -v131, v1, v18
	v_fmac_f32_e32 v19, v131, v0
	v_fmac_f32_e32 v2, v150, v0
	v_fmac_f32_e32 v19, v150, v1
	v_cvt_pk_bf16_f32 v0, v2, v19
	ds_write_b32 v155, v0 offset:14448
	s_waitcnt lgkmcnt(11)
	v_fma_f32 v0, -v131, v19, v20
	v_fma_f32 v1, v131, v2, v21
	v_fmac_f32_e32 v0, v150, v2
	v_fmac_f32_e32 v1, v150, v19
	v_cvt_pk_bf16_f32 v2, v0, v1
	ds_write_b32 v155, v2 offset:14720
	v_fma_f32 v2, -v131, v1, v22
	v_fmac_f32_e32 v23, v131, v0
	v_fmac_f32_e32 v2, v150, v0
	v_fmac_f32_e32 v23, v150, v1
	v_cvt_pk_bf16_f32 v0, v2, v23
	ds_write_b32 v155, v0 offset:14992
	s_waitcnt lgkmcnt(12)
	v_fma_f32 v0, -v131, v23, v24
	v_fma_f32 v1, v131, v2, v25
	v_fmac_f32_e32 v0, v150, v2
	v_fmac_f32_e32 v1, v150, v23
	v_cvt_pk_bf16_f32 v2, v0, v1
	ds_write_b32 v155, v2 offset:15264
	v_fma_f32 v2, -v131, v1, v26
	v_fmac_f32_e32 v27, v131, v0
	v_fmac_f32_e32 v2, v150, v0
	v_fmac_f32_e32 v27, v150, v1
	v_cvt_pk_bf16_f32 v0, v2, v27
	ds_write_b32 v155, v0 offset:15536
	s_waitcnt lgkmcnt(13)
	v_fma_f32 v0, -v131, v27, v28
	v_fma_f32 v1, v131, v2, v29
	v_fmac_f32_e32 v0, v150, v2
	v_fmac_f32_e32 v1, v150, v27
	v_cvt_pk_bf16_f32 v2, v0, v1
	ds_write_b32 v155, v2 offset:15808
	v_fma_f32 v2, -v131, v1, v30
	v_fmac_f32_e32 v31, v131, v0
	v_fmac_f32_e32 v2, v150, v0
	v_fmac_f32_e32 v31, v150, v1
	v_cvt_pk_bf16_f32 v0, v2, v31
	ds_write_b32 v155, v0 offset:16080
	s_waitcnt lgkmcnt(14)
	v_fma_f32 v0, -v131, v31, v98
	v_fma_f32 v1, v131, v2, v99
	v_fmac_f32_e32 v0, v150, v2
	v_fmac_f32_e32 v1, v150, v31
	v_fma_f32 v135, -v131, v1, v100
	v_fmac_f32_e32 v101, v131, v0
	v_cvt_pk_bf16_f32 v2, v0, v1
	v_fmac_f32_e32 v135, v150, v0
	v_fmac_f32_e32 v101, v150, v1
	ds_write_b32 v155, v2 offset:16352
	v_cvt_pk_bf16_f32 v0, v135, v101
	ds_write_b32 v155, v0 offset:16624
	ds_read_b128 v[0:3], v128 offset:8192
	ds_read_b128 v[16:19], v128 offset:8224
	s_waitcnt lgkmcnt(1)
	v_mfma_f32_32x32x16_bf16 v[0:15], v[0:3], v[90:93], 0
	ds_read_b128 v[32:35], v128 offset:8256
	ds_read_b128 v[36:39], v128 offset:8288
	s_waitcnt lgkmcnt(2)
	v_mfma_f32_32x32x16_bf16 v[16:31], v[16:19], v[86:89], 0
	s_waitcnt lgkmcnt(1)
	v_mfma_f32_32x32x16_bf16 v[0:15], v[32:35], v[82:85], v[0:15]
	s_waitcnt lgkmcnt(0)
	v_mfma_f32_32x32x16_bf16 v[16:31], v[36:39], v[78:81], v[16:31]
	ds_read_b128 v[32:35], v128 offset:8320
	ds_read_b128 v[36:39], v128 offset:8352
	s_waitcnt lgkmcnt(1)
	v_mfma_f32_32x32x16_bf16 v[0:15], v[32:35], v[74:77], v[0:15]
	s_waitcnt lgkmcnt(0)
	v_mfma_f32_32x32x16_bf16 v[16:31], v[36:39], v[70:73], v[16:31]
	ds_read_b128 v[32:35], v128 offset:8384
	ds_read_b128 v[36:39], v128 offset:8416
	s_waitcnt lgkmcnt(1)
	v_mfma_f32_32x32x16_bf16 v[0:15], v[32:35], v[66:69], v[0:15]
	s_waitcnt lgkmcnt(0)
	v_mfma_f32_32x32x16_bf16 v[16:31], v[36:39], v[62:65], v[16:31]
	s_and_saveexec_b64 s[46:47], vcc
	s_cbranch_execz .LBB0_624
	s_nop 9
	v_add_f32_e32 v0, v0, v16
	v_cvt_pk_bf16_f32 v0, v0, s0
	ds_write_b16 v153, v0
	v_add_f32_e32 v0, v1, v17
	v_cvt_pk_bf16_f32 v0, v0, s0
	ds_write_b16 v153, v0 offset:32
	v_add_f32_e32 v0, v2, v18
	v_cvt_pk_bf16_f32 v0, v0, s0
	ds_write_b16 v153, v0 offset:64
	v_add_f32_e32 v0, v3, v19
	v_cvt_pk_bf16_f32 v0, v0, s0
	ds_write_b16 v153, v0 offset:96
	v_add_f32_e32 v0, v4, v20
	v_cvt_pk_bf16_f32 v0, v0, s0
	ds_write_b16 v153, v0 offset:256
	v_add_f32_e32 v0, v5, v21
	v_cvt_pk_bf16_f32 v0, v0, s0
	ds_write_b16 v153, v0 offset:288
	v_add_f32_e32 v0, v6, v22
	v_cvt_pk_bf16_f32 v0, v0, s0
	ds_write_b16 v153, v0 offset:320
	v_add_f32_e32 v0, v7, v23
	v_cvt_pk_bf16_f32 v0, v0, s0
	ds_write_b16 v153, v0 offset:352
	v_add_f32_e32 v0, v8, v24
	v_cvt_pk_bf16_f32 v0, v0, s0
	ds_write_b16 v153, v0 offset:512
	v_add_f32_e32 v0, v9, v25
	v_cvt_pk_bf16_f32 v0, v0, s0
	ds_write_b16 v153, v0 offset:544
	v_add_f32_e32 v0, v10, v26
	v_cvt_pk_bf16_f32 v0, v0, s0
	ds_write_b16 v153, v0 offset:576
	v_add_f32_e32 v0, v11, v27
	v_cvt_pk_bf16_f32 v0, v0, s0
	ds_write_b16 v153, v0 offset:608
	v_add_f32_e32 v0, v12, v28
	v_cvt_pk_bf16_f32 v0, v0, s0
	ds_write_b16 v153, v0 offset:768
	v_add_f32_e32 v0, v13, v29
	v_cvt_pk_bf16_f32 v0, v0, s0
	ds_write_b16 v153, v0 offset:800
	v_add_f32_e32 v0, v14, v30
	v_cvt_pk_bf16_f32 v0, v0, s0
	ds_write_b16 v153, v0 offset:832
	v_add_f32_e32 v0, v15, v31
	v_cvt_pk_bf16_f32 v0, v0, s0
	ds_write_b16 v153, v0 offset:864
	s_branch .LBB0_624

.LBB0_927:
	s_andn2_b64 vcc, exec, s[44:45]
	s_cbranch_vccnz .LBB0_996
	v_readlane_b32 s48, v253, 2
	v_readlane_b32 s49, v253, 3
	v_mov_b32_e32 v6, v133
	v_mov_b32_e32 v0, v133
	v_readlane_b32 s3, v254, 55
	v_ashrrev_i32_e32 v8, 6, v0
	s_nop 0
	v_add_u32_e32 v24, s3, v8
	v_cmp_gt_i32_e32 vcc, s24, v24
	s_and_saveexec_b64 s[46:47], vcc
	s_cbranch_execz .LBB0_933
	s_load_dwordx2 s[44:45], s[48:49], 0xf8
	s_waitcnt lgkmcnt(0)
	s_load_dwordx4 s[52:55], s[48:49], 0x50
	v_ashrrev_i32_e32 v25, 31, v24
	v_lshlrev_b32_e32 v2, 2, v6
	v_lshlrev_b64 v[0:1], 11, v[24:25]
	v_and_b32_e32 v10, 0xfc, v2
	v_lshlrev_b32_e32 v128, 1, v10
	v_lshl_add_u64 v[0:1], s[44:45], 0, v[0:1]
	v_lshl_add_u64 v[2:3], v[0:1], 0, v[128:129]
	s_mov_b64 s[38:39], 0x13600000
	v_lshl_add_u64 v[4:5], v[2:3], 0, s[38:39]
	v_add_co_u32_e32 v2, vcc, s25, v2
	s_mul_i32 s3, s40, 0x36000
	s_nop 0
	v_addc_co_u32_e32 v3, vcc, 0, v3, vcc
	global_load_dwordx2 v[32:33], v[2:3], off
	global_load_dwordx2 v[30:31], v[4:5], off offset:512
	global_load_dwordx2 v[28:29], v[4:5], off offset:1024
	global_load_dwordx2 v[26:27], v[4:5], off offset:1536
	v_and_b32_e32 v2, 64, v188
	v_add_u32_e32 v2, 64, v2
	v_xor_b32_e32 v3, 32, v188
	v_cmp_lt_i32_e32 vcc, v3, v2
	s_add_u32 s3, s44, s3
	s_addc_u32 s30, s45, 0
	v_cndmask_b32_e32 v3, v188, v3, vcc
	v_lshlrev_b32_e32 v34, 2, v3
	v_xor_b32_e32 v3, 16, v188
	v_cmp_lt_i32_e32 vcc, v3, v2
	s_add_u32 s48, s3, 0x13403000
	s_addc_u32 s49, s30, 0
	v_cndmask_b32_e32 v3, v188, v3, vcc
	v_lshlrev_b32_e32 v35, 2, v3
	v_xor_b32_e32 v3, 8, v188
	v_cmp_lt_i32_e32 vcc, v3, v2
	s_lshl_b32 s80, s40, 11
	s_lshl_b64 s[38:39], s[80:81], 2
	v_cndmask_b32_e32 v3, v188, v3, vcc
	v_lshlrev_b32_e32 v36, 2, v3
	v_xor_b32_e32 v3, 4, v188
	v_cmp_lt_i32_e32 vcc, v3, v2
	s_waitcnt lgkmcnt(0)
	s_add_u32 s50, s54, s38
	v_readlane_b32 s3, v254, 56
	v_cndmask_b32_e32 v3, v188, v3, vcc
	v_lshlrev_b32_e32 v37, 2, v3
	v_xor_b32_e32 v3, 2, v188
	v_cmp_lt_i32_e32 vcc, v3, v2
	s_addc_u32 s51, s55, s39
	v_add_u32_e32 v8, s3, v8
	v_cndmask_b32_e32 v3, v188, v3, vcc
	v_lshlrev_b32_e32 v38, 2, v3
	v_xor_b32_e32 v3, 1, v188
	s_add_u32 s38, s52, s38
	v_cmp_lt_i32_e32 vcc, v3, v2
	v_ashrrev_i32_e32 v9, 31, v8
	s_addc_u32 s39, s53, s39
	v_cndmask_b32_e32 v2, v188, v3, vcc
	v_lshlrev_b32_e32 v128, 2, v10
	v_or_b32_e32 v12, 0x100, v10
	v_or_b32_e32 v14, 0x200, v10
	v_or_b32_e32 v16, 0x300, v10
	v_and_b32_e32 v6, 63, v6
	v_lshlrev_b64 v[8:9], 11, v[8:9]
	v_lshlrev_b32_e32 v39, 2, v2
	v_lshl_add_u64 v[2:3], s[38:39], 0, v[128:129]
	v_lshl_add_u64 v[4:5], s[50:51], 0, v[128:129]
	v_lshlrev_b32_e32 v6, 3, v6
	v_mov_b32_e32 v7, v129
	v_lshl_add_u64 v[8:9], s[44:45], 0, v[8:9]
	s_mov_b64 s[50:51], 0
	v_lshlrev_b32_e32 v128, 2, v10
	v_lshlrev_b32_e32 v10, 2, v12
	v_lshlrev_b32_e32 v12, 2, v14
	v_lshlrev_b32_e32 v14, 2, v16
	s_waitcnt vmcnt(0)
	s_branch .LBB0_931
.LBB0_930:
	s_or_b64 exec, exec, s[52:53]
	v_lshlrev_b32_e32 v54, 16, v32
	v_and_b32_e32 v55, 0xffff0000, v32
	v_add_f32_e32 v11, 0, v54
	v_lshlrev_b32_e32 v32, 16, v33
	v_add_f32_e32 v11, v11, v55
	v_and_b32_e32 v33, 0xffff0000, v33
	v_add_f32_e32 v11, v11, v32
	v_lshlrev_b32_e32 v56, 16, v30
	v_add_f32_e32 v11, v11, v33
	v_and_b32_e32 v57, 0xffff0000, v30
	v_add_f32_e32 v11, v11, v56
	v_lshlrev_b32_e32 v30, 16, v31
	v_add_f32_e32 v11, v11, v57
	v_and_b32_e32 v31, 0xffff0000, v31
	v_add_f32_e32 v11, v11, v30
	v_lshlrev_b32_e32 v58, 16, v28
	v_add_f32_e32 v11, v11, v31
	v_and_b32_e32 v59, 0xffff0000, v28
	v_add_f32_e32 v11, v11, v58
	v_lshlrev_b32_e32 v60, 16, v29
	v_add_f32_e32 v11, v11, v59
	v_and_b32_e32 v61, 0xffff0000, v29
	v_add_f32_e32 v11, v11, v60
	v_lshlrev_b32_e32 v62, 16, v26
	v_add_f32_e32 v11, v11, v61
	v_and_b32_e32 v63, 0xffff0000, v26
	v_add_f32_e32 v11, v11, v62
	v_lshlrev_b32_e32 v64, 16, v27
	v_add_f32_e32 v11, v11, v63
	v_and_b32_e32 v65, 0xffff0000, v27
	v_add_f32_e32 v11, v11, v64
	v_add_f32_e32 v11, v11, v65
	ds_bpermute_b32 v13, v34, v11
	v_cmp_lt_i32_e32 vcc, s22, v24
	s_and_b64 s[38:39], exec, s[44:45]
	s_or_b64 s[50:51], s[38:39], s[50:51]
	global_load_dwordx4 v[42:45], v[2:3], off
	global_load_dwordx4 v[46:49], v[4:5], off
	global_load_dwordx4 v[96:99], v[2:3], off offset:1024
	global_load_dwordx4 v[108:111], v[4:5], off offset:1024
	global_load_dwordx4 v[100:103], v[2:3], off offset:2048
	global_load_dwordx4 v[112:115], v[4:5], off offset:2048
	global_load_dwordx4 v[104:107], v[2:3], off offset:3072
	global_load_dwordx4 v[116:119], v[4:5], off offset:3072
	s_waitcnt lgkmcnt(0)
	v_add_f32_e32 v11, v11, v13
	ds_bpermute_b32 v13, v35, v11
	v_lshl_add_u64 v[78:79], v[0:1], 0, v[6:7]
	s_mov_b32 s3, 0x1d600000
	v_mov_b32_e32 v15, v129
	v_lshl_add_u64 v[8:9], v[8:9], 0, s[4:5]
	s_waitcnt lgkmcnt(0)
	v_add_f32_e32 v11, v11, v13
	ds_bpermute_b32 v13, v36, v11
	v_lshl_add_u64 v[0:1], v[0:1], 0, s[4:5]
	s_waitcnt lgkmcnt(0)
	v_add_f32_e32 v11, v11, v13
	ds_bpermute_b32 v13, v37, v11
	s_waitcnt lgkmcnt(0)
	v_add_f32_e32 v11, v11, v13
	ds_bpermute_b32 v13, v38, v11
	s_waitcnt lgkmcnt(0)
	v_add_f32_e32 v11, v11, v13
	ds_bpermute_b32 v13, v39, v11
	s_waitcnt lgkmcnt(0)
	v_add_f32_e32 v11, v11, v13
	v_mul_f32_e32 v66, 0x3a800000, v11
	v_add_u32_e32 v11, 0xffffe000, v24
	v_lshrrev_b32_e32 v11, 12, v11
	v_add_u32_e32 v11, 1, v11
	v_cndmask_b32_e32 v11, 0, v11, vcc
	v_mov_b64_e32 v[24:25], s[48:49]
	v_mad_u64_u32 v[24:25], s[38:39], v11, s23, v[24:25]
	s_mov_b64 s[38:39], 0x1000
	s_nop 0
	v_lshl_add_u64 v[68:69], v[24:25], 0, s[38:39]
	v_lshl_add_u64 v[24:25], v[24:25], 0, v[128:129]
	v_lshl_add_u64 v[26:27], v[68:69], 0, v[128:129]
	global_load_dwordx4 v[50:53], v[24:25], off
	v_pk_add_f32 v[54:55], v[54:55], v[66:67] op_sel_hi:[1,0] neg_lo:[0,1] neg_hi:[0,1]
	global_load_dwordx4 v[120:123], v[24:25], off offset:1024
	global_load_dwordx4 v[140:143], v[26:27], off offset:1024
	global_load_dwordx4 v[124:127], v[24:25], off offset:2048
	global_load_dwordx4 v[144:147], v[26:27], off offset:2048
	global_load_dwordx4 v[136:139], v[24:25], off offset:3072
	global_load_dwordx4 v[148:151], v[26:27], off offset:3072
	global_load_dwordx4 v[26:29], v[26:27], off
	v_pk_add_f32 v[32:33], v[32:33], v[66:67] op_sel_hi:[1,0] neg_lo:[0,1] neg_hi:[0,1]
	v_pk_mul_f32 v[72:73], v[54:55], v[54:55]
	v_mov_b32_e32 v11, v129
	v_pk_mul_f32 v[70:71], v[32:33], v[32:33]
	v_lshl_add_u64 v[80:81], v[68:69], 0, v[10:11]
	v_add_f32_e32 v11, v72, v73
	v_pk_add_f32 v[56:57], v[56:57], v[66:67] op_sel_hi:[1,0] neg_lo:[0,1] neg_hi:[0,1]
	v_add_f32_e32 v11, v70, v11
	v_pk_mul_f32 v[86:87], v[56:57], v[56:57]
	v_add_f32_e32 v11, v71, v11
	v_pk_add_f32 v[82:83], v[30:31], v[66:67] op_sel_hi:[1,0] neg_lo:[0,1] neg_hi:[0,1]
	v_add_f32_e32 v11, v86, v11
	v_pk_mul_f32 v[84:85], v[82:83], v[82:83]
	v_add_f32_e32 v11, v87, v11
	v_pk_add_f32 v[58:59], v[58:59], v[66:67] op_sel_hi:[1,0] neg_lo:[0,1] neg_hi:[0,1]
	v_add_f32_e32 v11, v84, v11
	v_pk_mul_f32 v[92:93], v[58:59], v[58:59]
	v_add_f32_e32 v11, v85, v11
	v_pk_add_f32 v[60:61], v[60:61], v[66:67] op_sel_hi:[1,0] neg_lo:[0,1] neg_hi:[0,1]
	v_add_f32_e32 v11, v92, v11
	v_pk_mul_f32 v[90:91], v[60:61], v[60:61]
	v_add_f32_e32 v11, v93, v11
	v_pk_add_f32 v[30:31], v[62:63], v[66:67] op_sel_hi:[1,0] neg_lo:[0,1] neg_hi:[0,1]
	v_add_f32_e32 v11, v90, v11
	v_pk_mul_f32 v[62:63], v[30:31], v[30:31]
	v_add_f32_e32 v11, v91, v11
	v_add_f32_e32 v11, v62, v11
	v_add_f32_e32 v11, v63, v11
	v_mov_b32_e32 v13, v129
	v_lshl_add_u64 v[88:89], v[68:69], 0, v[12:13]
	s_waitcnt vmcnt(0)
	v_pk_add_f32 v[76:77], v[28:29], 1.0 op_sel_hi:[1,0]
	v_pk_add_f32 v[28:29], v[64:65], v[66:67] op_sel_hi:[1,0] neg_lo:[0,1] neg_hi:[0,1]
	v_pk_add_f32 v[74:75], v[26:27], 1.0 op_sel_hi:[1,0]
	v_pk_mul_f32 v[64:65], v[28:29], v[28:29]
	v_lshl_add_u64 v[26:27], v[68:69], 0, v[14:15]
	v_add_f32_e32 v11, v64, v11
	v_add_f32_e32 v11, v65, v11
	ds_bpermute_b32 v13, v34, v11
	s_waitcnt lgkmcnt(0)
	v_add_f32_e32 v11, v11, v13
	ds_bpermute_b32 v13, v35, v11
	s_waitcnt lgkmcnt(0)
	v_add_f32_e32 v11, v11, v13
	ds_bpermute_b32 v13, v36, v11
	s_waitcnt lgkmcnt(0)
	v_add_f32_e32 v11, v11, v13
	ds_bpermute_b32 v13, v37, v11
	s_waitcnt lgkmcnt(0)
	v_add_f32_e32 v11, v11, v13
	ds_bpermute_b32 v13, v38, v11
	s_waitcnt lgkmcnt(0)
	v_add_f32_e32 v11, v11, v13
	ds_bpermute_b32 v13, v39, v11
	s_waitcnt lgkmcnt(0)
	v_add_f32_e32 v11, v11, v13
	v_fmamk_f32 v11, v11, 0x3a800000, v182
	v_cmp_gt_f32_e32 vcc, s13, v11
	v_mul_f32_e32 v13, 0x4b800000, v11
	s_nop 0
	v_cndmask_b32_e32 v11, v11, v13, vcc
	v_rsq_f32_e32 v11, v11
	s_nop 0
	v_mul_f32_e32 v13, 0x45800000, v11
	v_cndmask_b32_e32 v62, v11, v13, vcc
	v_pk_mul_f32 v[54:55], v[54:55], v[62:63] op_sel_hi:[1,0]
	v_pk_mul_f32 v[32:33], v[32:33], v[62:63] op_sel_hi:[1,0]
	v_pk_fma_f32 v[42:43], v[42:43], v[54:55], v[46:47]
	v_pk_fma_f32 v[32:33], v[44:45], v[32:33], v[48:49]
	v_pk_fma_f32 v[44:45], v[74:75], v[42:43], v[50:51]
	v_pk_fma_f32 v[46:47], v[76:77], v[32:33], v[52:53]
	v_cvt_pk_bf16_f32 v42, v42, v43
	v_cvt_pk_bf16_f32 v43, v32, v33
	v_add_co_u32_e32 v32, vcc, s25, v78
	v_pk_mul_f32 v[52:53], v[56:57], v[62:63] op_sel_hi:[1,0]
	s_nop 0
	v_addc_co_u32_e32 v33, vcc, 0, v79, vcc
	v_add_co_u32_e32 v50, vcc, s3, v78
	global_store_dwordx2 v[32:33], v[42:43], off
	v_cvt_pk_bf16_f32 v42, v44, v45
	v_cvt_pk_bf16_f32 v43, v46, v47
	v_addc_co_u32_e32 v51, vcc, 0, v79, vcc
	global_store_dwordx2 v[50:51], v[42:43], off
	v_pk_mul_f32 v[152:153], v[56:57], v[62:63] op_sel_hi:[1,0]
	v_pk_mul_f32 v[154:155], v[82:83], v[62:63] op_sel_hi:[1,0]
	v_pk_add_f32 v[156:157], v[140:141], 1.0 op_sel_hi:[1,0]
	v_pk_add_f32 v[158:159], v[142:143], 1.0 op_sel_hi:[1,0]
	v_pk_fma_f32 v[152:153], v[96:97], v[152:153], v[108:109]
	v_pk_fma_f32 v[154:155], v[98:99], v[154:155], v[110:111]
	s_nop 0
	v_pk_fma_f32 v[160:161], v[156:157], v[152:153], v[120:121]
	v_pk_fma_f32 v[162:163], v[158:159], v[154:155], v[122:123]
	v_cvt_pk_bf16_f32 v196, v152, v153
	v_cvt_pk_bf16_f32 v197, v154, v155
	v_cvt_pk_bf16_f32 v198, v160, v161
	v_cvt_pk_bf16_f32 v199, v162, v163
	global_store_dwordx2 v[32:33], v[196:197], off offset:512
	global_store_dwordx2 v[50:51], v[198:199], off offset:512
	v_pk_mul_f32 v[152:153], v[58:59], v[62:63] op_sel_hi:[1,0]
	v_pk_mul_f32 v[154:155], v[60:61], v[62:63] op_sel_hi:[1,0]
	v_pk_add_f32 v[156:157], v[144:145], 1.0 op_sel_hi:[1,0]
	v_pk_add_f32 v[158:159], v[146:147], 1.0 op_sel_hi:[1,0]
	v_pk_fma_f32 v[152:153], v[100:101], v[152:153], v[112:113]
	v_pk_fma_f32 v[154:155], v[102:103], v[154:155], v[114:115]
	s_nop 0
	v_pk_fma_f32 v[160:161], v[156:157], v[152:153], v[124:125]
	v_pk_fma_f32 v[162:163], v[158:159], v[154:155], v[126:127]
	v_cvt_pk_bf16_f32 v200, v152, v153
	v_cvt_pk_bf16_f32 v201, v154, v155
	v_cvt_pk_bf16_f32 v202, v160, v161
	v_cvt_pk_bf16_f32 v203, v162, v163
	global_store_dwordx2 v[32:33], v[200:201], off offset:1024
	global_store_dwordx2 v[50:51], v[202:203], off offset:1024
	v_pk_mul_f32 v[152:153], v[30:31], v[62:63] op_sel_hi:[1,0]
	v_pk_mul_f32 v[154:155], v[28:29], v[62:63] op_sel_hi:[1,0]
	v_pk_add_f32 v[156:157], v[148:149], 1.0 op_sel_hi:[1,0]
	v_pk_add_f32 v[158:159], v[150:151], 1.0 op_sel_hi:[1,0]
	v_pk_fma_f32 v[152:153], v[104:105], v[152:153], v[116:117]
	v_pk_fma_f32 v[154:155], v[106:107], v[154:155], v[118:119]
	s_nop 0
	v_pk_fma_f32 v[160:161], v[156:157], v[152:153], v[136:137]
	v_pk_fma_f32 v[162:163], v[158:159], v[154:155], v[138:139]
	v_cvt_pk_bf16_f32 v204, v152, v153
	v_cvt_pk_bf16_f32 v205, v154, v155
	v_cvt_pk_bf16_f32 v206, v160, v161
	v_cvt_pk_bf16_f32 v207, v162, v163
	global_store_dwordx2 v[32:33], v[204:205], off offset:1536
	global_store_dwordx2 v[50:51], v[206:207], off offset:1536
	v_mov_b32_e32 v24, v40
	v_mov_b32_e32 v32, v18
	v_mov_b32_e32 v33, v19
	v_mov_b32_e32 v30, v20
	v_mov_b32_e32 v31, v21
	v_mov_b32_e32 v28, v22
	v_mov_b32_e32 v29, v23
	v_mov_b32_e32 v26, v16
	v_mov_b32_e32 v27, v17
	s_andn2_b64 exec, exec, s[50:51]
	s_cbranch_execz .LBB0_933
.LBB0_931:
	v_add_u32_e32 v40, s84, v24
	v_cmp_gt_i32_e32 vcc, s24, v40
	v_cmp_lt_i32_e64 s[44:45], s26, v40
	v_mov_b32_e32 v18, v32
	v_mov_b32_e32 v19, v33
	v_mov_b32_e32 v20, v30
	v_mov_b32_e32 v21, v31
	v_mov_b32_e32 v22, v28
	v_mov_b32_e32 v23, v29
	v_mov_b32_e32 v16, v26
	v_mov_b32_e32 v17, v27
	s_and_saveexec_b64 s[52:53], vcc
	s_cbranch_execz .LBB0_930
	v_lshl_add_u64 v[16:17], v[8:9], 0, v[6:7]
	v_add_co_u32_e32 v16, vcc, 0x13600000, v16
	s_nop 1
	v_addc_co_u32_e32 v17, vcc, 0, v17, vcc
	global_load_dwordx2 v[18:19], v[16:17], off
	global_load_dwordx2 v[20:21], v[16:17], off offset:512
	global_load_dwordx2 v[22:23], v[16:17], off offset:1024
	s_nop 0
	global_load_dwordx2 v[16:17], v[16:17], off offset:1536
	s_branch .LBB0_930

.LBB0_1004:
	s_and_b32 s77, s76, 1
	s_mul_i32 s78, s77, 0x4800
	v_lshl_add_u64 v[96:97], v[160:161], 0, s[58:59]
	v_lshl_add_u64 v[100:101], v[168:169], 0, s[58:59]
	v_lshl_add_u64 v[104:105], v[162:163], 0, s[58:59]
	v_lshl_add_u64 v[108:109], v[170:171], 0, s[58:59]
	v_lshl_add_u64 v[112:113], v[164:165], 0, s[58:59]
	v_lshl_add_u64 v[116:117], v[172:173], 0, s[58:59]
	v_lshl_add_u64 v[120:121], v[166:167], 0, s[58:59]
	v_lshl_add_u64 v[124:125], v[174:175], 0, s[58:59]
	v_add3_u32 v197, s78, v232, v231
	global_load_dwordx4 v[96:99], v[96:97], off
	s_nop 0
	global_load_dwordx4 v[100:103], v[100:101], off
	s_nop 0
	global_load_dwordx4 v[104:107], v[104:105], off
	s_nop 0
	global_load_dwordx4 v[108:111], v[108:109], off
	s_nop 0
	global_load_dwordx4 v[112:115], v[112:113], off
	s_nop 0
	global_load_dwordx4 v[116:119], v[116:117], off
	s_nop 0
	global_load_dwordx4 v[120:123], v[120:121], off
	s_nop 0
	global_load_dwordx4 v[124:127], v[124:125], off
	v_add3_u32 v198, s78, v234, v231
	ds_read_b128 v[242:245], v198 offset:36864
	ds_read_b128 v[238:241], v197
	ds_read_b128 v[246:249], v197 offset:4608
	ds_read_b128 v[200:203], v197 offset:9216
	ds_read_b128 v[204:207], v197 offset:13824
	s_waitcnt lgkmcnt(3)
	v_mfma_f32_32x32x16_bf16 v[48:63], v[238:241], v[242:245], v[48:63]
	ds_read_b128 v[208:211], v198 offset:36896
	ds_read_b128 v[238:241], v197 offset:32
	s_add_i32 s76, s76, 1
	s_xor_b32 s79, s77, 1
	s_xor_b32 s80, s77, 3
	s_mul_i32 s77, s79, 0x4800
	s_add_u32 s58, s58, 0x80
	s_mul_i32 s78, s80, 0x4800
	s_waitcnt lgkmcnt(4)
	v_mfma_f32_32x32x16_bf16 v[32:47], v[246:249], v[242:245], v[32:47]
	ds_read_b128 v[246:249], v197 offset:4640
	v_or_b32_e32 v250, s77, v128
	s_addc_u32 s59, s59, 0
	v_or_b32_e32 v251, s78, v128
	v_add_u32_e32 v252, v250, v233
	s_cmpk_lg_i32 s58, 0x780
	v_add_u32_e32 v177, v251, v233
	s_waitcnt lgkmcnt(4)
	v_mfma_f32_32x32x16_bf16 v[16:31], v[200:203], v[242:245], v[16:31]
	ds_read_b128 v[200:203], v197 offset:9248
	s_waitcnt lgkmcnt(4)
	v_mfma_f32_32x32x16_bf16 v[0:15], v[204:207], v[242:245], v[0:15]
	ds_read_b128 v[204:207], v197 offset:13856
	s_waitcnt lgkmcnt(3)
	v_mfma_f32_32x32x16_bf16 v[48:63], v[238:241], v[208:211], v[48:63]
	ds_read_b128 v[242:245], v198 offset:36928
	ds_read_b128 v[238:241], v197 offset:64
	s_waitcnt lgkmcnt(4)
	v_mfma_f32_32x32x16_bf16 v[32:47], v[246:249], v[208:211], v[32:47]
	ds_read_b128 v[246:249], v197 offset:4672
	s_waitcnt lgkmcnt(4)
	v_mfma_f32_32x32x16_bf16 v[16:31], v[200:203], v[208:211], v[16:31]
	ds_read_b128 v[200:203], v197 offset:9280
	s_waitcnt lgkmcnt(4)
	v_mfma_f32_32x32x16_bf16 v[0:15], v[204:207], v[208:211], v[0:15]
	ds_read_b128 v[204:207], v197 offset:13888
	s_waitcnt lgkmcnt(3)
	v_mfma_f32_32x32x16_bf16 v[48:63], v[238:241], v[242:245], v[48:63]
	ds_read_b128 v[208:211], v198 offset:36960
	ds_read_b128 v[238:241], v197 offset:96
	s_waitcnt lgkmcnt(4)
	v_mfma_f32_32x32x16_bf16 v[32:47], v[246:249], v[242:245], v[32:47]
	ds_read_b128 v[246:249], v197 offset:4704
	s_waitcnt lgkmcnt(4)
	v_mfma_f32_32x32x16_bf16 v[16:31], v[200:203], v[242:245], v[16:31]
	ds_read_b128 v[200:203], v197 offset:9312
	s_waitcnt lgkmcnt(4)
	v_mfma_f32_32x32x16_bf16 v[0:15], v[204:207], v[242:245], v[0:15]
	ds_read_b128 v[204:207], v197 offset:13920
	s_waitcnt lgkmcnt(3)
	v_mfma_f32_32x32x16_bf16 v[48:63], v[238:241], v[208:211], v[48:63]
	s_waitcnt lgkmcnt(2)
	v_mfma_f32_32x32x16_bf16 v[32:47], v[246:249], v[208:211], v[32:47]
	s_waitcnt lgkmcnt(1)
	v_mfma_f32_32x32x16_bf16 v[16:31], v[200:203], v[208:211], v[16:31]
	v_add_u32_e32 v238, v250, v235
	v_add_u32_e32 v239, v251, v235
	v_add_u32_e32 v240, v250, v236
	v_add_u32_e32 v241, v251, v236
	v_add_u32_e32 v250, v250, v237
	v_add_u32_e32 v251, v251, v237
	s_waitcnt vmcnt(7)
	ds_write_b128 v252, v[96:99]
	s_waitcnt vmcnt(6)
	ds_write_b128 v177, v[100:103]
	s_waitcnt vmcnt(5)
	ds_write_b128 v238, v[104:107]
	s_waitcnt vmcnt(4)
	ds_write_b128 v239, v[108:111]
	s_waitcnt vmcnt(3)
	ds_write_b128 v240, v[112:115]
	s_waitcnt vmcnt(2)
	ds_write_b128 v241, v[116:119]
	s_waitcnt vmcnt(1)
	ds_write_b128 v250, v[120:123]
	s_waitcnt vmcnt(0)
	ds_write_b128 v251, v[124:127]
	s_waitcnt lgkmcnt(8)
	v_mfma_f32_32x32x16_bf16 v[0:15], v[204:207], v[208:211], v[0:15]
	s_waitcnt lgkmcnt(0)
	s_barrier
	s_cbranch_scc1 .LBB0_1004
	v_or_b32_e32 v197, 0x61, v193
	v_or_b32_e32 v198, 0x62, v193
	v_or_b32_e32 v199, 0x63, v193
	v_or_b32_e32 v200, 0x68, v193
	v_or_b32_e32 v201, 0x69, v193
	v_or_b32_e32 v202, 0x6a, v193
	v_or_b32_e32 v203, 0x6b, v193
	v_or_b32_e32 v204, 0x70, v193
	v_or_b32_e32 v205, 0x71, v193
	v_or_b32_e32 v206, 0x72, v193
	v_or_b32_e32 v207, 0x73, v193
	v_or_b32_e32 v208, 0x78, v193
	v_or_b32_e32 v209, 0x79, v193
	v_or_b32_e32 v210, 0x7a, v193
	v_or_b32_e32 v211, 0x7b, v193
	v_add_u32_e32 v108, v232, v231
	ds_read_b128 v[96:99], v108 offset:18432
	v_add_u32_e32 v104, v234, v231
	ds_read_b128 v[100:103], v104 offset:55296
	s_mov_b32 s80, 1
	s_mov_b64 s[58:59], 0
	s_waitcnt lgkmcnt(0)
	v_mfma_f32_32x32x16_bf16 v[48:63], v[96:99], v[100:103], v[48:63]
	ds_read_b128 v[96:99], v108 offset:23040
	s_waitcnt lgkmcnt(0)
	v_mfma_f32_32x32x16_bf16 v[32:47], v[96:99], v[100:103], v[32:47]
	ds_read_b128 v[96:99], v108 offset:27648
	s_waitcnt lgkmcnt(0)
	v_mfma_f32_32x32x16_bf16 v[16:31], v[96:99], v[100:103], v[16:31]
	ds_read_b128 v[96:99], v108 offset:32256
	s_waitcnt lgkmcnt(0)
	v_mfma_f32_32x32x16_bf16 v[0:15], v[96:99], v[100:103], v[0:15]
	ds_read_b128 v[96:99], v108 offset:18464
	ds_read_b128 v[100:103], v104 offset:55328
	s_waitcnt lgkmcnt(0)
	v_mfma_f32_32x32x16_bf16 v[48:63], v[96:99], v[100:103], v[48:63]
	ds_read_b128 v[96:99], v108 offset:23072
	s_waitcnt lgkmcnt(0)
	v_mfma_f32_32x32x16_bf16 v[32:47], v[96:99], v[100:103], v[32:47]
	ds_read_b128 v[96:99], v108 offset:27680
	s_waitcnt lgkmcnt(0)
	v_mfma_f32_32x32x16_bf16 v[16:31], v[96:99], v[100:103], v[16:31]
	ds_read_b128 v[96:99], v108 offset:32288
	s_waitcnt lgkmcnt(0)
	v_mfma_f32_32x32x16_bf16 v[0:15], v[96:99], v[100:103], v[0:15]
	ds_read_b128 v[96:99], v108 offset:18496
	ds_read_b128 v[100:103], v104 offset:55360
	s_waitcnt lgkmcnt(0)
	v_mfma_f32_32x32x16_bf16 v[48:63], v[96:99], v[100:103], v[48:63]
	ds_read_b128 v[96:99], v108 offset:23104
	s_waitcnt lgkmcnt(0)
	v_mfma_f32_32x32x16_bf16 v[32:47], v[96:99], v[100:103], v[32:47]
	ds_read_b128 v[96:99], v108 offset:27712
	s_waitcnt lgkmcnt(0)
	v_mfma_f32_32x32x16_bf16 v[16:31], v[96:99], v[100:103], v[16:31]
	ds_read_b128 v[96:99], v108 offset:32320
	s_waitcnt lgkmcnt(0)
	v_mfma_f32_32x32x16_bf16 v[0:15], v[96:99], v[100:103], v[0:15]
	ds_read_b128 v[96:99], v108 offset:18528
	ds_read_b128 v[100:103], v104 offset:55392
	s_waitcnt lgkmcnt(0)
	v_mfma_f32_32x32x16_bf16 v[48:63], v[96:99], v[100:103], v[48:63]
	ds_read_b128 v[96:99], v108 offset:23136
	ds_read_b128 v[104:107], v108 offset:27744
	ds_read_b128 v[108:111], v108 offset:32352
	s_waitcnt lgkmcnt(0)
	s_barrier
	ds_write_b128 v212, v[64:67]
	ds_write_b128 v213, v[68:71]
	ds_write_b128 v214, v[72:75]
	ds_write_b128 v215, v[76:79]
	ds_write_b128 v216, v[80:83]
	ds_write_b128 v217, v[84:87]
	ds_write_b128 v218, v[88:91]
	ds_write_b128 v219, v[92:95]
	s_waitcnt lgkmcnt(0)
	s_barrier
	ds_read2_b64 v[64:67], v196 offset1:2
	v_cvt_pk_bf16_f32 v80, v48, v49
	v_cvt_pk_bf16_f32 v81, v50, v51
	v_cvt_pk_bf16_f32 v82, v52, v53
	v_cvt_pk_bf16_f32 v83, v54, v55
	ds_read2_b64 v[48:51], v196 offset0:4 offset1:6
	v_cvt_pk_bf16_f32 v56, v56, v57
	s_waitcnt lgkmcnt(1)
	v_mfma_f32_32x32x16_bf16 v[64:79], v[64:67], v[80:83], 0
	v_cvt_pk_bf16_f32 v57, v58, v59
	v_cvt_pk_bf16_f32 v58, v60, v61
	v_cvt_pk_bf16_f32 v59, v62, v63
	v_add_u32_e32 v94, 0x4000, v196
	ds_read2_b64 v[90:93], v94 offset0:132 offset1:134
	v_mfma_f32_32x32x16_bf16 v[32:47], v[96:99], v[100:103], v[32:47]
	s_waitcnt lgkmcnt(1)
	v_mfma_f32_32x32x16_bf16 v[64:79], v[48:51], v[56:59], v[64:79]
	ds_read2_b64 v[48:51], v196 offset0:8 offset1:10
	s_nop 8
	v_cvt_pk_bf16_f32 v52, v32, v33
	v_cvt_pk_bf16_f32 v53, v34, v35
	v_cvt_pk_bf16_f32 v54, v36, v37
	v_cvt_pk_bf16_f32 v55, v38, v39
	ds_read2_b64 v[32:35], v196 offset0:12 offset1:14
	s_waitcnt lgkmcnt(1)
	v_mfma_f32_32x32x16_bf16 v[64:79], v[48:51], v[52:55], v[64:79]
	v_cvt_pk_bf16_f32 v48, v40, v41
	v_cvt_pk_bf16_f32 v49, v42, v43
	v_cvt_pk_bf16_f32 v50, v44, v45
	v_cvt_pk_bf16_f32 v51, v46, v47
	v_mfma_f32_32x32x16_bf16 v[16:31], v[104:107], v[100:103], v[16:31]
	s_waitcnt lgkmcnt(0)
	v_mfma_f32_32x32x16_bf16 v[64:79], v[32:35], v[48:51], v[64:79]
	ds_read2_b64 v[32:35], v196 offset0:16 offset1:18
	s_nop 8
	v_cvt_pk_bf16_f32 v44, v16, v17
	v_cvt_pk_bf16_f32 v45, v18, v19
	v_cvt_pk_bf16_f32 v46, v20, v21
	v_cvt_pk_bf16_f32 v47, v22, v23
	ds_read2_b64 v[16:19], v196 offset0:20 offset1:22
	v_cvt_pk_bf16_f32 v40, v24, v25
	s_waitcnt lgkmcnt(1)
	v_mfma_f32_32x32x16_bf16 v[64:79], v[32:35], v[44:47], v[64:79]
	v_cvt_pk_bf16_f32 v41, v26, v27
	v_cvt_pk_bf16_f32 v42, v28, v29
	v_cvt_pk_bf16_f32 v43, v30, v31
	v_add_u32_e32 v24, 0x2000, v196
	v_or_b32_e32 v22, 9, v193
	v_mfma_f32_32x32x16_bf16 v[0:15], v[108:111], v[100:103], v[0:15]
	v_add_u32_e32 v100, 0x6000, v196
	s_waitcnt lgkmcnt(0)
	v_mfma_f32_32x32x16_bf16 v[64:79], v[16:19], v[40:43], v[64:79]
	ds_read2_b64 v[16:19], v196 offset0:24 offset1:26
	s_nop 7
	v_cvt_pk_bf16_f32 v36, v0, v1
	v_cvt_pk_bf16_f32 v37, v2, v3
	v_cvt_pk_bf16_f32 v38, v4, v5
	v_cvt_pk_bf16_f32 v39, v6, v7
	ds_read2_b64 v[0:3], v196 offset0:28 offset1:30
	v_cvt_pk_bf16_f32 v32, v8, v9
	s_waitcnt lgkmcnt(1)
	v_mfma_f32_32x32x16_bf16 v[64:79], v[16:19], v[36:39], v[64:79]
	v_cvt_pk_bf16_f32 v33, v10, v11
	v_cvt_pk_bf16_f32 v34, v12, v13
	v_cvt_pk_bf16_f32 v35, v14, v15
	v_or_b32_e32 v6, 3, v193
	ds_read2_b64 v[16:19], v24 offset0:68 offset1:70
	s_waitcnt lgkmcnt(1)
	v_mfma_f32_32x32x16_bf16 v[64:79], v[0:3], v[32:35], v[64:79]
	v_or_b32_e32 v2, 1, v193
	s_nop 10
	v_ashrrev_i32_e32 v1, 31, v64
	v_and_b32_e32 v0, 0xffffff80, v64
	v_and_b32_e32 v1, 0x7fffffff, v1
	v_bitop3_b32 v60, v0, v1, v193 bitop3:0x36
	v_ashrrev_i32_e32 v1, 31, v65
	v_and_b32_e32 v0, 0xffffff80, v65
	v_and_b32_e32 v1, 0x7fffffff, v1
	v_bitop3_b32 v61, v0, v1, v2 bitop3:0x36
	v_ashrrev_i32_e32 v1, 31, v66
	v_and_b32_e32 v0, 0xffffff80, v66
	v_and_b32_e32 v1, 0x7fffffff, v1
	v_or_b32_e32 v2, 2, v193
	v_bitop3_b32 v62, v0, v1, v2 bitop3:0x36
	ds_read2_b64 v[0:3], v24 offset0:64 offset1:66
	v_ashrrev_i32_e32 v5, 31, v67
	v_and_b32_e32 v4, 0xffffff80, v67
	v_and_b32_e32 v5, 0x7fffffff, v5
	v_bitop3_b32 v63, v4, v5, v6 bitop3:0x36
	v_ashrrev_i32_e32 v5, 31, v68
	v_and_b32_e32 v4, 0xffffff80, v68
	v_and_b32_e32 v5, 0x7fffffff, v5
	v_or_b32_e32 v6, 8, v193
	v_bitop3_b32 v64, v4, v5, v6 bitop3:0x36
	s_waitcnt lgkmcnt(0)
	v_mfma_f32_32x32x16_bf16 v[0:15], v[0:3], v[80:83], 0
	v_ashrrev_i32_e32 v21, 31, v69
	v_and_b32_e32 v20, 0xffffff80, v69
	v_and_b32_e32 v21, 0x7fffffff, v21
	v_bitop3_b32 v68, v20, v21, v22 bitop3:0x36
	v_ashrrev_i32_e32 v20, 31, v70
	v_and_b32_e32 v26, 0x7fffffff, v20
	ds_read2_b64 v[20:23], v24 offset0:72 offset1:74
	v_mfma_f32_32x32x16_bf16 v[0:15], v[16:19], v[56:59], v[0:15]
	v_and_b32_e32 v25, 0xffffff80, v70
	v_or_b32_e32 v16, 10, v193
	v_ashrrev_i32_e32 v17, 31, v71
	v_bitop3_b32 v69, v25, v26, v16 bitop3:0x36
	v_and_b32_e32 v16, 0xffffff80, v71
	v_and_b32_e32 v17, 0x7fffffff, v17
	v_or_b32_e32 v18, 11, v193
	v_bitop3_b32 v70, v16, v17, v18 bitop3:0x36
	ds_read2_b64 v[16:19], v24 offset0:76 offset1:78
	s_waitcnt lgkmcnt(1)
	v_mfma_f32_32x32x16_bf16 v[0:15], v[20:23], v[52:55], v[0:15]
	v_ashrrev_i32_e32 v20, 31, v72
	v_and_b32_e32 v25, 0xffffff80, v72
	v_and_b32_e32 v20, 0x7fffffff, v20
	v_or_b32_e32 v21, 16, v193
	v_bitop3_b32 v71, v25, v20, v21 bitop3:0x36
	v_ashrrev_i32_e32 v20, 31, v73
	v_and_b32_e32 v26, 0x7fffffff, v20
	ds_read2_b64 v[20:23], v24 offset0:80 offset1:82
	s_waitcnt lgkmcnt(1)
	v_mfma_f32_32x32x16_bf16 v[0:15], v[16:19], v[48:51], v[0:15]
	v_and_b32_e32 v25, 0xffffff80, v73
	v_or_b32_e32 v16, 17, v193
	v_ashrrev_i32_e32 v17, 31, v74
	v_bitop3_b32 v72, v25, v26, v16 bitop3:0x36
	v_and_b32_e32 v16, 0xffffff80, v74
	v_and_b32_e32 v17, 0x7fffffff, v17
	v_or_b32_e32 v18, 18, v193
	v_bitop3_b32 v74, v16, v17, v18 bitop3:0x36
	ds_read2_b64 v[16:19], v24 offset0:84 offset1:86
	s_waitcnt lgkmcnt(1)
	v_mfma_f32_32x32x16_bf16 v[0:15], v[20:23], v[44:47], v[0:15]
	v_ashrrev_i32_e32 v20, 31, v75
	v_and_b32_e32 v25, 0xffffff80, v75
	v_and_b32_e32 v20, 0x7fffffff, v20
	v_or_b32_e32 v21, 19, v193
	v_bitop3_b32 v84, v25, v20, v21 bitop3:0x36
	v_ashrrev_i32_e32 v20, 31, v76
	v_and_b32_e32 v26, 0x7fffffff, v20
	ds_read2_b64 v[20:23], v24 offset0:88 offset1:90
	s_waitcnt lgkmcnt(1)
	v_mfma_f32_32x32x16_bf16 v[0:15], v[16:19], v[40:43], v[0:15]
	v_and_b32_e32 v25, 0xffffff80, v76
	v_or_b32_e32 v16, 24, v193
	v_ashrrev_i32_e32 v17, 31, v77
	v_bitop3_b32 v85, v25, v26, v16 bitop3:0x36
	v_and_b32_e32 v16, 0xffffff80, v77
	v_and_b32_e32 v17, 0x7fffffff, v17
	v_or_b32_e32 v18, 25, v193
	v_bitop3_b32 v86, v16, v17, v18 bitop3:0x36
	ds_read2_b64 v[16:19], v24 offset0:92 offset1:94
	s_waitcnt lgkmcnt(1)
	v_mfma_f32_32x32x16_bf16 v[0:15], v[20:23], v[36:39], v[0:15]
	v_ashrrev_i32_e32 v20, 31, v78
	v_and_b32_e32 v25, 0xffffff80, v78
	v_and_b32_e32 v20, 0x7fffffff, v20
	v_or_b32_e32 v21, 26, v193
	v_bitop3_b32 v87, v25, v20, v21 bitop3:0x36
	v_ashrrev_i32_e32 v21, 31, v79
	v_and_b32_e32 v20, 0xffffff80, v79
	s_waitcnt lgkmcnt(0)
	v_mfma_f32_32x32x16_bf16 v[0:15], v[16:19], v[32:35], v[0:15]
	v_or_b32_e32 v17, 32, v193
	v_or_b32_e32 v18, 35, v193
	v_and_b32_e32 v21, 0x7fffffff, v21
	v_or_b32_e32 v22, 27, v193
	v_bitop3_b32 v88, v20, v21, v22 bitop3:0x36
	s_nop 6
	v_and_b32_e32 v16, 0xffffff80, v0
	v_ashrrev_i32_e32 v0, 31, v0
	v_and_b32_e32 v0, 0x7fffffff, v0
	v_bitop3_b32 v65, v16, v0, v17 bitop3:0x36
	v_and_b32_e32 v0, 0xffffff80, v1
	v_ashrrev_i32_e32 v1, 31, v1
	v_and_b32_e32 v1, 0x7fffffff, v1
	v_or_b32_e32 v16, 33, v193
	v_bitop3_b32 v66, v0, v1, v16 bitop3:0x36
	v_ashrrev_i32_e32 v1, 31, v2
	v_and_b32_e32 v0, 0xffffff80, v2
	v_and_b32_e32 v1, 0x7fffffff, v1
	v_or_b32_e32 v2, 34, v193
	v_bitop3_b32 v67, v0, v1, v2 bitop3:0x36
	v_and_b32_e32 v16, 0xffffff80, v3
	v_ashrrev_i32_e32 v17, 31, v3
	ds_read2_b64 v[0:3], v94 offset0:128 offset1:130
	v_and_b32_e32 v17, 0x7fffffff, v17
	v_bitop3_b32 v73, v16, v17, v18 bitop3:0x36
	v_and_b32_e32 v16, 0xffffff80, v4
	v_ashrrev_i32_e32 v4, 31, v4
	v_and_b32_e32 v4, 0x7fffffff, v4
	v_or_b32_e32 v17, 40, v193
	v_bitop3_b32 v75, v16, v4, v17 bitop3:0x36
	s_waitcnt lgkmcnt(0)
	v_mfma_f32_32x32x16_bf16 v[16:31], v[0:3], v[80:83], 0
	v_ashrrev_i32_e32 v0, 31, v5
	v_and_b32_e32 v4, 0xffffff80, v5
	v_and_b32_e32 v0, 0x7fffffff, v0
	v_or_b32_e32 v1, 41, v193
	v_bitop3_b32 v76, v4, v0, v1 bitop3:0x36
	v_ashrrev_i32_e32 v0, 31, v6
	v_and_b32_e32 v5, 0x7fffffff, v0
	ds_read2_b64 v[0:3], v94 offset0:136 offset1:138
	v_mfma_f32_32x32x16_bf16 v[16:31], v[90:93], v[56:59], v[16:31]
	v_and_b32_e32 v4, 0xffffff80, v6
	v_or_b32_e32 v6, 42, v193
	v_bitop3_b32 v77, v4, v5, v6 bitop3:0x36
	v_ashrrev_i32_e32 v5, 31, v7
	v_and_b32_e32 v4, 0xffffff80, v7
	v_and_b32_e32 v5, 0x7fffffff, v5
	v_or_b32_e32 v6, 43, v193
	v_bitop3_b32 v78, v4, v5, v6 bitop3:0x36
	ds_read2_b64 v[4:7], v94 offset0:140 offset1:142
	s_waitcnt lgkmcnt(1)
	v_mfma_f32_32x32x16_bf16 v[16:31], v[0:3], v[52:55], v[16:31]
	v_ashrrev_i32_e32 v0, 31, v8
	v_and_b32_e32 v79, 0xffffff80, v8
	v_and_b32_e32 v0, 0x7fffffff, v0
	v_or_b32_e32 v1, 48, v193
	v_bitop3_b32 v79, v79, v0, v1 bitop3:0x36
	v_ashrrev_i32_e32 v0, 31, v9
	v_and_b32_e32 v8, 0xffffff80, v9
	v_and_b32_e32 v9, 0x7fffffff, v0
	ds_read2_b64 v[0:3], v94 offset0:144 offset1:146
	s_waitcnt lgkmcnt(1)
	v_mfma_f32_32x32x16_bf16 v[16:31], v[4:7], v[48:51], v[16:31]
	v_or_b32_e32 v4, 49, v193
	v_ashrrev_i32_e32 v5, 31, v10
	v_bitop3_b32 v89, v8, v9, v4 bitop3:0x36
	v_and_b32_e32 v4, 0xffffff80, v10
	v_and_b32_e32 v5, 0x7fffffff, v5
	v_or_b32_e32 v6, 50, v193
	v_bitop3_b32 v90, v4, v5, v6 bitop3:0x36
	ds_read2_b64 v[4:7], v94 offset0:148 offset1:150
	s_waitcnt lgkmcnt(1)
	v_mfma_f32_32x32x16_bf16 v[16:31], v[0:3], v[44:47], v[16:31]
	v_ashrrev_i32_e32 v0, 31, v11
	v_and_b32_e32 v8, 0xffffff80, v11
	v_and_b32_e32 v0, 0x7fffffff, v0
	v_or_b32_e32 v1, 51, v193
	v_bitop3_b32 v91, v8, v0, v1 bitop3:0x36
	v_ashrrev_i32_e32 v0, 31, v12
	v_and_b32_e32 v9, 0x7fffffff, v0
	ds_read2_b64 v[0:3], v94 offset0:152 offset1:154
	s_waitcnt lgkmcnt(1)
	v_mfma_f32_32x32x16_bf16 v[16:31], v[4:7], v[40:43], v[16:31]
	v_and_b32_e32 v8, 0xffffff80, v12
	v_or_b32_e32 v4, 56, v193
	v_ashrrev_i32_e32 v5, 31, v13
	v_bitop3_b32 v96, v8, v9, v4 bitop3:0x36
	v_and_b32_e32 v4, 0xffffff80, v13
	v_and_b32_e32 v5, 0x7fffffff, v5
	v_or_b32_e32 v6, 57, v193
	v_bitop3_b32 v97, v4, v5, v6 bitop3:0x36
	ds_read2_b64 v[4:7], v94 offset0:156 offset1:158
	s_waitcnt lgkmcnt(1)
	v_mfma_f32_32x32x16_bf16 v[16:31], v[0:3], v[36:39], v[16:31]
	v_ashrrev_i32_e32 v0, 31, v14
	v_and_b32_e32 v8, 0xffffff80, v14
	v_and_b32_e32 v0, 0x7fffffff, v0
	v_or_b32_e32 v1, 58, v193
	v_bitop3_b32 v98, v8, v0, v1 bitop3:0x36
	v_ashrrev_i32_e32 v1, 31, v15
	v_and_b32_e32 v0, 0xffffff80, v15
	s_waitcnt lgkmcnt(0)
	v_mfma_f32_32x32x16_bf16 v[16:31], v[4:7], v[32:35], v[16:31]
	v_and_b32_e32 v1, 0x7fffffff, v1
	v_or_b32_e32 v2, 59, v193
	v_bitop3_b32 v99, v0, v1, v2 bitop3:0x36
	v_or_b32_e32 v2, 64, v193
	v_or_b32_e32 v6, 0x43, v193
	ds_read2_b64 v[92:95], v100 offset0:196 offset1:198
	s_nop 5
	v_ashrrev_i32_e32 v1, 31, v16
	v_and_b32_e32 v0, 0xffffff80, v16
	v_and_b32_e32 v1, 0x7fffffff, v1
	v_bitop3_b32 v16, v0, v1, v2 bitop3:0x36
	v_ashrrev_i32_e32 v1, 31, v17
	v_and_b32_e32 v0, 0xffffff80, v17
	v_and_b32_e32 v1, 0x7fffffff, v1
	v_or_b32_e32 v2, 0x41, v193
	v_bitop3_b32 v17, v0, v1, v2 bitop3:0x36
	v_ashrrev_i32_e32 v1, 31, v18
	v_and_b32_e32 v0, 0xffffff80, v18
	v_and_b32_e32 v1, 0x7fffffff, v1
	v_or_b32_e32 v2, 0x42, v193
	v_bitop3_b32 v18, v0, v1, v2 bitop3:0x36
	ds_read2_b64 v[0:3], v100 offset0:192 offset1:194
	v_ashrrev_i32_e32 v5, 31, v19
	v_and_b32_e32 v4, 0xffffff80, v19
	v_and_b32_e32 v5, 0x7fffffff, v5
	v_bitop3_b32 v19, v4, v5, v6 bitop3:0x36
	v_ashrrev_i32_e32 v5, 31, v20
	v_and_b32_e32 v4, 0xffffff80, v20
	v_and_b32_e32 v5, 0x7fffffff, v5
	v_or_b32_e32 v6, 0x48, v193
	v_bitop3_b32 v20, v4, v5, v6 bitop3:0x36
	s_waitcnt lgkmcnt(0)
	v_mfma_f32_32x32x16_bf16 v[0:15], v[0:3], v[80:83], 0
	v_and_b32_e32 v101, 0xffffff80, v21
	v_ashrrev_i32_e32 v21, 31, v21
	v_and_b32_e32 v21, 0x7fffffff, v21
	v_or_b32_e32 v80, 0x49, v193
	v_bitop3_b32 v21, v101, v21, v80 bitop3:0x36
	ds_read2_b64 v[80:83], v100 offset0:200 offset1:202
	v_and_b32_e32 v101, 0xffffff80, v22
	v_mfma_f32_32x32x16_bf16 v[0:15], v[92:95], v[56:59], v[0:15]
	v_ashrrev_i32_e32 v22, 31, v22
	v_and_b32_e32 v22, 0x7fffffff, v22
	v_or_b32_e32 v56, 0x4a, v193
	v_bitop3_b32 v92, v101, v22, v56 bitop3:0x36
	v_and_b32_e32 v22, 0xffffff80, v23
	v_ashrrev_i32_e32 v23, 31, v23
	v_and_b32_e32 v23, 0x7fffffff, v23
	v_or_b32_e32 v56, 0x4b, v193
	v_bitop3_b32 v93, v22, v23, v56 bitop3:0x36
	ds_read2_b64 v[56:59], v100 offset0:204 offset1:206
	s_waitcnt lgkmcnt(1)
	v_mfma_f32_32x32x16_bf16 v[0:15], v[80:83], v[52:55], v[0:15]
	v_ashrrev_i32_e32 v23, 31, v24
	v_and_b32_e32 v22, 0xffffff80, v24
	v_and_b32_e32 v23, 0x7fffffff, v23
	v_or_b32_e32 v24, 0x50, v193
	v_bitop3_b32 v52, v22, v23, v24 bitop3:0x36
	v_ashrrev_i32_e32 v22, 31, v25
	v_and_b32_e32 v53, 0xffffff80, v25
	v_and_b32_e32 v54, 0x7fffffff, v22
	ds_read2_b64 v[22:25], v100 offset0:208 offset1:210
	s_waitcnt lgkmcnt(1)
	v_mfma_f32_32x32x16_bf16 v[0:15], v[56:59], v[48:51], v[0:15]
	v_or_b32_e32 v48, 0x51, v193
	v_bitop3_b32 v53, v53, v54, v48 bitop3:0x36
	v_and_b32_e32 v48, 0xffffff80, v26
	v_ashrrev_i32_e32 v26, 31, v26
	v_and_b32_e32 v26, 0x7fffffff, v26
	v_or_b32_e32 v49, 0x52, v193
	v_bitop3_b32 v54, v48, v26, v49 bitop3:0x36
	ds_read2_b64 v[48:51], v100 offset0:212 offset1:214
	s_waitcnt lgkmcnt(1)
	v_mfma_f32_32x32x16_bf16 v[0:15], v[22:25], v[44:47], v[0:15]
	v_ashrrev_i32_e32 v22, 31, v27
	v_and_b32_e32 v26, 0xffffff80, v27
	v_and_b32_e32 v22, 0x7fffffff, v22
	v_or_b32_e32 v23, 0x53, v193
	v_bitop3_b32 v44, v26, v22, v23 bitop3:0x36
	v_ashrrev_i32_e32 v22, 31, v28
	v_and_b32_e32 v27, 0x7fffffff, v22
	ds_read2_b64 v[22:25], v100 offset0:216 offset1:218
	s_waitcnt lgkmcnt(1)
	v_mfma_f32_32x32x16_bf16 v[0:15], v[48:51], v[40:43], v[0:15]
	v_and_b32_e32 v26, 0xffffff80, v28
	v_or_b32_e32 v28, 0x58, v193
	v_bitop3_b32 v40, v26, v27, v28 bitop3:0x36
	v_ashrrev_i32_e32 v27, 31, v29
	v_and_b32_e32 v26, 0xffffff80, v29
	v_and_b32_e32 v27, 0x7fffffff, v27
	v_or_b32_e32 v28, 0x59, v193
	v_bitop3_b32 v41, v26, v27, v28 bitop3:0x36
	ds_read2_b64 v[26:29], v100 offset0:220 offset1:222
	s_waitcnt lgkmcnt(1)
	v_mfma_f32_32x32x16_bf16 v[0:15], v[22:25], v[36:39], v[0:15]
	v_ashrrev_i32_e32 v22, 31, v30
	v_and_b32_e32 v42, 0xffffff80, v30
	v_and_b32_e32 v22, 0x7fffffff, v22
	v_or_b32_e32 v23, 0x5a, v193
	v_ashrrev_i32_e32 v24, 31, v31
	v_bitop3_b32 v22, v42, v22, v23 bitop3:0x36
	v_and_b32_e32 v23, 0xffffff80, v31
	s_waitcnt lgkmcnt(0)
	v_mfma_f32_32x32x16_bf16 v[0:15], v[26:29], v[32:35], v[0:15]
	v_and_b32_e32 v24, 0x7fffffff, v24
	v_or_b32_e32 v25, 0x5b, v193
	v_bitop3_b32 v23, v23, v24, v25 bitop3:0x36
	v_or_b32_e32 v25, 0x60, v193
	v_max_i32_e32 v26, v63, v62
	v_min_i32_e32 v27, v63, v62
	v_max_i32_e32 v28, v64, v68
	s_nop 4
	v_and_b32_e32 v24, 0xffffff80, v0
	v_ashrrev_i32_e32 v0, 31, v0
	v_and_b32_e32 v0, 0x7fffffff, v0
	v_bitop3_b32 v0, v24, v0, v25 bitop3:0x36
	v_and_b32_e32 v24, 0xffffff80, v1
	v_ashrrev_i32_e32 v1, 31, v1
	v_and_b32_e32 v1, 0x7fffffff, v1
	v_bitop3_b32 v1, v24, v1, v197 bitop3:0x36
	v_and_b32_e32 v24, 0xffffff80, v2
	v_ashrrev_i32_e32 v2, 31, v2
	v_and_b32_e32 v2, 0x7fffffff, v2
	v_bitop3_b32 v2, v24, v2, v198 bitop3:0x36
	v_and_b32_e32 v24, 0xffffff80, v3
	v_ashrrev_i32_e32 v3, 31, v3
	v_and_b32_e32 v3, 0x7fffffff, v3
	v_bitop3_b32 v3, v24, v3, v199 bitop3:0x36
	v_and_b32_e32 v24, 0xffffff80, v4
	v_ashrrev_i32_e32 v4, 31, v4
	v_and_b32_e32 v4, 0x7fffffff, v4
	v_bitop3_b32 v4, v24, v4, v200 bitop3:0x36
	v_and_b32_e32 v24, 0xffffff80, v5
	v_ashrrev_i32_e32 v5, 31, v5
	v_and_b32_e32 v5, 0x7fffffff, v5
	v_bitop3_b32 v5, v24, v5, v201 bitop3:0x36
	v_and_b32_e32 v24, 0xffffff80, v6
	v_ashrrev_i32_e32 v6, 31, v6
	v_and_b32_e32 v6, 0x7fffffff, v6
	v_bitop3_b32 v6, v24, v6, v202 bitop3:0x36
	v_and_b32_e32 v24, 0xffffff80, v7
	v_ashrrev_i32_e32 v7, 31, v7
	v_and_b32_e32 v7, 0x7fffffff, v7
	v_bitop3_b32 v7, v24, v7, v203 bitop3:0x36
	v_and_b32_e32 v24, 0xffffff80, v8
	v_ashrrev_i32_e32 v8, 31, v8
	v_and_b32_e32 v8, 0x7fffffff, v8
	v_bitop3_b32 v8, v24, v8, v204 bitop3:0x36
	v_and_b32_e32 v24, 0xffffff80, v9
	v_ashrrev_i32_e32 v9, 31, v9
	v_and_b32_e32 v9, 0x7fffffff, v9
	v_bitop3_b32 v9, v24, v9, v205 bitop3:0x36
	v_and_b32_e32 v24, 0xffffff80, v10
	v_ashrrev_i32_e32 v10, 31, v10
	v_and_b32_e32 v10, 0x7fffffff, v10
	v_bitop3_b32 v10, v24, v10, v206 bitop3:0x36
	v_and_b32_e32 v24, 0xffffff80, v11
	v_ashrrev_i32_e32 v11, 31, v11
	v_and_b32_e32 v11, 0x7fffffff, v11
	v_bitop3_b32 v11, v24, v11, v207 bitop3:0x36
	v_and_b32_e32 v24, 0xffffff80, v12
	v_ashrrev_i32_e32 v12, 31, v12
	v_and_b32_e32 v12, 0x7fffffff, v12
	v_bitop3_b32 v12, v24, v12, v208 bitop3:0x36
	v_and_b32_e32 v24, 0xffffff80, v13
	v_ashrrev_i32_e32 v13, 31, v13
	v_and_b32_e32 v13, 0x7fffffff, v13
	v_bitop3_b32 v13, v24, v13, v209 bitop3:0x36
	v_and_b32_e32 v24, 0xffffff80, v14
	v_ashrrev_i32_e32 v14, 31, v14
	v_and_b32_e32 v14, 0x7fffffff, v14
	v_bitop3_b32 v14, v24, v14, v210 bitop3:0x36
	v_and_b32_e32 v24, 0xffffff80, v15
	v_ashrrev_i32_e32 v15, 31, v15
	v_and_b32_e32 v15, 0x7fffffff, v15
	v_bitop3_b32 v15, v24, v15, v211 bitop3:0x36
	v_max_i32_e32 v24, v60, v61
	v_min_i32_e32 v25, v60, v61
	v_min_i32_e32 v29, v64, v68
	v_max_i32_e32 v30, v70, v69
	v_min_i32_e32 v31, v70, v69
	v_max_i32_e32 v32, v71, v72
	v_min_i32_e32 v33, v71, v72
	v_max_i32_e32 v34, v84, v74
	v_min_i32_e32 v35, v84, v74
	v_max_i32_e32 v36, v85, v86
	v_min_i32_e32 v37, v85, v86
	v_max_i32_e32 v38, v88, v87
	v_min_i32_e32 v39, v88, v87
	v_max_i32_e32 v51, v65, v66
	v_min_i32_e32 v55, v65, v66
	v_max_i32_e32 v56, v73, v67
	v_min_i32_e32 v57, v73, v67
	v_max_i32_e32 v58, v75, v76
	v_min_i32_e32 v59, v75, v76
	v_max_i32_e32 v60, v78, v77
	v_min_i32_e32 v61, v78, v77
	v_max_i32_e32 v62, v79, v89
	v_min_i32_e32 v63, v79, v89
	v_max_i32_e32 v64, v91, v90
	v_min_i32_e32 v65, v91, v90
	v_max_i32_e32 v66, v96, v97
	v_min_i32_e32 v67, v96, v97
	v_max_i32_e32 v68, v99, v98
	v_min_i32_e32 v69, v99, v98
	v_max_i32_e32 v78, v16, v17
	v_min_i32_e32 v16, v16, v17
	v_max_i32_e32 v17, v19, v18
	v_min_i32_e32 v18, v19, v18
	v_max_i32_e32 v19, v20, v21
	v_min_i32_e32 v20, v20, v21
	v_max_i32_e32 v21, v93, v92
	v_min_i32_e32 v79, v93, v92
	v_max_i32_e32 v80, v52, v53
	v_min_i32_e32 v52, v52, v53
	v_max_i32_e32 v53, v44, v54
	v_min_i32_e32 v44, v44, v54
	v_max_i32_e32 v54, v40, v41
	v_min_i32_e32 v40, v40, v41
	v_max_i32_e32 v41, v23, v22
	v_min_i32_e32 v22, v23, v22
	v_max_i32_e32 v88, v0, v1
	v_min_i32_e32 v0, v0, v1
	v_max_i32_e32 v1, v3, v2
	v_min_i32_e32 v2, v3, v2
	v_max_i32_e32 v3, v4, v5
	v_min_i32_e32 v4, v4, v5
	v_max_i32_e32 v5, v7, v6
	v_min_i32_e32 v6, v7, v6
	v_max_i32_e32 v7, v8, v9
	v_min_i32_e32 v8, v8, v9
	v_max_i32_e32 v9, v11, v10
	v_min_i32_e32 v10, v11, v10
	v_max_i32_e32 v11, v12, v13
	v_min_i32_e32 v12, v12, v13
	v_max_i32_e32 v13, v15, v14
	v_min_i32_e32 v14, v15, v14
	v_max_i32_e32 v42, v24, v27
	v_min_i32_e32 v24, v24, v27
	v_max_i32_e32 v27, v25, v26
	v_min_i32_e32 v25, v25, v26
	v_max_i32_e32 v26, v31, v28
	v_min_i32_e32 v28, v31, v28
	v_max_i32_e32 v31, v30, v29
	v_min_i32_e32 v29, v30, v29
	v_max_i32_e32 v30, v32, v35
	v_min_i32_e32 v32, v32, v35
	v_max_i32_e32 v35, v33, v34
	v_min_i32_e32 v33, v33, v34
	v_max_i32_e32 v34, v39, v36
	v_min_i32_e32 v36, v39, v36
	v_max_i32_e32 v39, v38, v37
	v_min_i32_e32 v37, v38, v37
	v_max_i32_e32 v70, v51, v57
	v_min_i32_e32 v51, v51, v57
	v_max_i32_e32 v57, v55, v56
	v_min_i32_e32 v55, v55, v56
	v_max_i32_e32 v56, v61, v58
	v_min_i32_e32 v58, v61, v58
	v_max_i32_e32 v61, v60, v59
	v_min_i32_e32 v59, v60, v59
	v_max_i32_e32 v60, v62, v65
	v_min_i32_e32 v62, v62, v65
	v_max_i32_e32 v65, v63, v64
	v_min_i32_e32 v63, v63, v64
	v_max_i32_e32 v64, v69, v66
	v_min_i32_e32 v66, v69, v66
	v_max_i32_e32 v69, v68, v67
	v_min_i32_e32 v67, v68, v67
	v_max_i32_e32 v23, v78, v18
	v_min_i32_e32 v18, v78, v18
	v_max_i32_e32 v78, v16, v17
	v_min_i32_e32 v16, v16, v17
	v_max_i32_e32 v17, v79, v19
	v_min_i32_e32 v19, v79, v19
	v_max_i32_e32 v79, v21, v20
	v_min_i32_e32 v20, v21, v20
	v_max_i32_e32 v21, v80, v44
	v_min_i32_e32 v44, v80, v44
	v_max_i32_e32 v80, v52, v53
	v_min_i32_e32 v52, v52, v53
	v_max_i32_e32 v53, v22, v54
	v_min_i32_e32 v22, v22, v54
	v_max_i32_e32 v54, v41, v40
	v_min_i32_e32 v40, v41, v40
	v_max_i32_e32 v15, v88, v2
	v_min_i32_e32 v2, v88, v2
	v_max_i32_e32 v88, v0, v1
	v_min_i32_e32 v0, v0, v1
	v_max_i32_e32 v1, v6, v3
	v_min_i32_e32 v3, v6, v3
	v_max_i32_e32 v6, v5, v4
	v_min_i32_e32 v4, v5, v4
	v_max_i32_e32 v5, v7, v10
	v_min_i32_e32 v7, v7, v10
	v_max_i32_e32 v10, v8, v9
	v_min_i32_e32 v8, v8, v9
	v_max_i32_e32 v9, v14, v11
	v_min_i32_e32 v11, v14, v11
	v_max_i32_e32 v14, v13, v12
	v_min_i32_e32 v12, v13, v12
	v_max_i32_e32 v38, v42, v27
	v_min_i32_e32 v27, v42, v27
	v_max_i32_e32 v42, v24, v25
	v_min_i32_e32 v24, v24, v25
	v_max_i32_e32 v25, v29, v28
	v_min_i32_e32 v28, v29, v28
	v_max_i32_e32 v29, v31, v26
	v_min_i32_e32 v26, v31, v26
	v_max_i32_e32 v31, v30, v35
	v_min_i32_e32 v30, v30, v35
	v_max_i32_e32 v35, v32, v33
	v_min_i32_e32 v32, v32, v33
	v_max_i32_e32 v33, v37, v36
	v_min_i32_e32 v36, v37, v36
	v_max_i32_e32 v37, v39, v34
	v_min_i32_e32 v34, v39, v34
	v_max_i32_e32 v68, v70, v57
	v_min_i32_e32 v57, v70, v57
	v_max_i32_e32 v70, v51, v55
	v_min_i32_e32 v51, v51, v55
	v_max_i32_e32 v55, v59, v58
	v_min_i32_e32 v58, v59, v58
	v_max_i32_e32 v59, v61, v56
	v_min_i32_e32 v56, v61, v56
	v_max_i32_e32 v61, v60, v65
	v_min_i32_e32 v60, v60, v65
	v_max_i32_e32 v65, v62, v63
	v_min_i32_e32 v62, v62, v63
	v_max_i32_e32 v63, v67, v66
	v_min_i32_e32 v66, v67, v66
	v_max_i32_e32 v67, v69, v64
	v_min_i32_e32 v64, v69, v64
	v_max_i32_e32 v41, v23, v78
	v_min_i32_e32 v23, v23, v78
	v_max_i32_e32 v78, v18, v16
	v_min_i32_e32 v16, v18, v16
	v_max_i32_e32 v18, v20, v19
	v_min_i32_e32 v19, v20, v19
	v_max_i32_e32 v20, v79, v17
	v_min_i32_e32 v17, v79, v17
	v_max_i32_e32 v79, v21, v80
	v_min_i32_e32 v21, v21, v80
	v_max_i32_e32 v80, v44, v52
	v_min_i32_e32 v44, v44, v52
	v_max_i32_e32 v52, v40, v22
	v_min_i32_e32 v22, v40, v22
	v_max_i32_e32 v40, v54, v53
	v_min_i32_e32 v53, v54, v53
	v_max_i32_e32 v13, v15, v88
	v_min_i32_e32 v15, v15, v88
	v_max_i32_e32 v88, v2, v0
	v_min_i32_e32 v0, v2, v0
	v_max_i32_e32 v2, v4, v3
	v_min_i32_e32 v3, v4, v3
	v_max_i32_e32 v4, v6, v1
	v_min_i32_e32 v1, v6, v1
	v_max_i32_e32 v6, v5, v10
	v_min_i32_e32 v5, v5, v10
	v_max_i32_e32 v10, v7, v8
	v_min_i32_e32 v7, v7, v8
	v_max_i32_e32 v8, v12, v11
	v_min_i32_e32 v11, v12, v11
	v_max_i32_e32 v12, v14, v9
	v_min_i32_e32 v9, v14, v9
	v_max_i32_e32 v39, v38, v28
	v_min_i32_e32 v28, v38, v28
	v_max_i32_e32 v38, v27, v25
	v_min_i32_e32 v25, v27, v25
	v_max_i32_e32 v27, v42, v26
	v_min_i32_e32 v26, v42, v26
	v_max_i32_e32 v42, v24, v29
	v_min_i32_e32 v24, v24, v29
	v_max_i32_e32 v29, v36, v31
	v_min_i32_e32 v31, v36, v31
	v_max_i32_e32 v36, v33, v30
	v_min_i32_e32 v30, v33, v30
	v_max_i32_e32 v33, v34, v35
	v_min_i32_e32 v34, v34, v35
	v_max_i32_e32 v35, v37, v32
	v_min_i32_e32 v32, v37, v32
	v_max_i32_e32 v69, v68, v58
	v_min_i32_e32 v58, v68, v58
	v_max_i32_e32 v68, v57, v55
	v_min_i32_e32 v55, v57, v55
	v_max_i32_e32 v57, v70, v56
	v_min_i32_e32 v56, v70, v56
	v_max_i32_e32 v70, v51, v59
	v_min_i32_e32 v51, v51, v59
	v_max_i32_e32 v59, v66, v61
	v_min_i32_e32 v61, v66, v61
	v_max_i32_e32 v66, v63, v60
	v_min_i32_e32 v60, v63, v60
	v_max_i32_e32 v63, v64, v65
	v_min_i32_e32 v64, v64, v65
	v_max_i32_e32 v65, v67, v62
	v_min_i32_e32 v62, v67, v62
	v_max_i32_e32 v54, v41, v19
	v_min_i32_e32 v19, v41, v19
	v_max_i32_e32 v41, v23, v18
	v_min_i32_e32 v18, v23, v18
	v_max_i32_e32 v23, v78, v17
	v_min_i32_e32 v17, v78, v17
	v_max_i32_e32 v78, v16, v20
	v_min_i32_e32 v16, v16, v20
	v_max_i32_e32 v20, v22, v79
	v_min_i32_e32 v22, v22, v79
	v_max_i32_e32 v79, v52, v21
	v_min_i32_e32 v21, v52, v21
	v_max_i32_e32 v52, v53, v80
	v_min_i32_e32 v53, v53, v80
	v_max_i32_e32 v80, v40, v44
	v_min_i32_e32 v40, v40, v44
	v_max_i32_e32 v14, v13, v3
	v_min_i32_e32 v3, v13, v3
	v_max_i32_e32 v13, v15, v2
	v_min_i32_e32 v2, v15, v2
	v_max_i32_e32 v15, v88, v1
	v_min_i32_e32 v1, v88, v1
	v_max_i32_e32 v88, v0, v4
	v_min_i32_e32 v0, v0, v4
	v_max_i32_e32 v4, v11, v6
	v_min_i32_e32 v6, v11, v6
	v_max_i32_e32 v11, v8, v5
	v_min_i32_e32 v5, v8, v5
	v_max_i32_e32 v8, v9, v10
	v_min_i32_e32 v9, v9, v10
	v_max_i32_e32 v10, v12, v7
	v_min_i32_e32 v7, v12, v7
	v_max_i32_e32 v37, v39, v27
	v_min_i32_e32 v27, v39, v27
	v_max_i32_e32 v39, v38, v42
	v_min_i32_e32 v38, v38, v42
	v_max_i32_e32 v42, v28, v26
	v_min_i32_e32 v26, v28, v26
	v_max_i32_e32 v28, v25, v24
	v_min_i32_e32 v24, v25, v24
	v_max_i32_e32 v25, v34, v31
	v_min_i32_e32 v31, v34, v31
	v_max_i32_e32 v34, v32, v30
	v_min_i32_e32 v30, v32, v30
	v_max_i32_e32 v32, v33, v29
	v_min_i32_e32 v29, v33, v29
	v_max_i32_e32 v33, v35, v36
	v_min_i32_e32 v35, v35, v36
	v_max_i32_e32 v67, v69, v57
	v_min_i32_e32 v57, v69, v57
	v_max_i32_e32 v69, v68, v70
	v_min_i32_e32 v68, v68, v70
	v_max_i32_e32 v70, v58, v56
	v_min_i32_e32 v56, v58, v56
	v_max_i32_e32 v58, v55, v51
	v_min_i32_e32 v51, v55, v51
	v_max_i32_e32 v55, v64, v61
	v_min_i32_e32 v61, v64, v61
	v_max_i32_e32 v64, v62, v60
	v_min_i32_e32 v60, v62, v60
	v_max_i32_e32 v62, v63, v59
	v_min_i32_e32 v59, v63, v59
	v_max_i32_e32 v63, v65, v66
	v_min_i32_e32 v65, v65, v66
	v_max_i32_e32 v44, v54, v23
	v_min_i32_e32 v23, v54, v23
	v_max_i32_e32 v54, v41, v78
	v_min_i32_e32 v41, v41, v78
	v_max_i32_e32 v78, v19, v17
	v_min_i32_e32 v17, v19, v17
	v_max_i32_e32 v19, v18, v16
	v_min_i32_e32 v16, v18, v16
	v_max_i32_e32 v18, v53, v22
	v_min_i32_e32 v22, v53, v22
	v_max_i32_e32 v53, v40, v21
	v_min_i32_e32 v21, v40, v21
	v_max_i32_e32 v40, v52, v20
	v_min_i32_e32 v20, v52, v20
	v_max_i32_e32 v52, v80, v79
	v_min_i32_e32 v79, v80, v79
	v_max_i32_e32 v12, v14, v15
	v_min_i32_e32 v14, v14, v15
	v_max_i32_e32 v15, v13, v88
	v_min_i32_e32 v13, v13, v88
	v_max_i32_e32 v88, v3, v1
	v_min_i32_e32 v1, v3, v1
	v_max_i32_e32 v3, v2, v0
	v_min_i32_e32 v0, v2, v0
	v_max_i32_e32 v2, v9, v6
	v_min_i32_e32 v6, v9, v6
	v_max_i32_e32 v9, v7, v5
	v_min_i32_e32 v5, v7, v5
	v_max_i32_e32 v7, v8, v4
	v_min_i32_e32 v4, v8, v4
	v_max_i32_e32 v8, v10, v11
	v_min_i32_e32 v10, v10, v11
	v_max_i32_e32 v36, v37, v39
	v_min_i32_e32 v37, v37, v39
	v_max_i32_e32 v39, v27, v38
	v_min_i32_e32 v27, v27, v38
	v_max_i32_e32 v38, v42, v28
	v_min_i32_e32 v28, v42, v28
	v_max_i32_e32 v42, v26, v24
	v_min_i32_e32 v24, v26, v24
	v_max_i32_e32 v26, v30, v31
	v_min_i32_e32 v30, v30, v31
	v_max_i32_e32 v31, v34, v25
	v_min_i32_e32 v25, v34, v25
	v_max_i32_e32 v34, v35, v29
	v_min_i32_e32 v29, v35, v29
	v_max_i32_e32 v35, v33, v32
	v_min_i32_e32 v32, v33, v32
	v_max_i32_e32 v66, v67, v69
	v_min_i32_e32 v67, v67, v69
	v_max_i32_e32 v69, v57, v68
	v_min_i32_e32 v57, v57, v68
	v_max_i32_e32 v68, v70, v58
	v_min_i32_e32 v58, v70, v58
	v_max_i32_e32 v70, v56, v51
	v_min_i32_e32 v51, v56, v51
	v_max_i32_e32 v56, v60, v61
	v_min_i32_e32 v60, v60, v61
	v_max_i32_e32 v61, v64, v55
	v_min_i32_e32 v55, v64, v55
	v_max_i32_e32 v64, v65, v59
	v_min_i32_e32 v59, v65, v59
	v_max_i32_e32 v65, v63, v62
	v_min_i32_e32 v62, v63, v62
	v_max_i32_e32 v80, v44, v54
	v_min_i32_e32 v44, v44, v54
	v_max_i32_e32 v54, v23, v41
	v_min_i32_e32 v23, v23, v41
	v_max_i32_e32 v41, v78, v19
	v_min_i32_e32 v19, v78, v19
	v_max_i32_e32 v78, v17, v16
	v_min_i32_e32 v16, v17, v16
	v_max_i32_e32 v17, v21, v22
	v_min_i32_e32 v21, v21, v22
	v_max_i32_e32 v22, v53, v18
	v_min_i32_e32 v18, v53, v18
	v_max_i32_e32 v53, v79, v20
	v_min_i32_e32 v20, v79, v20
	v_max_i32_e32 v79, v52, v40
	v_min_i32_e32 v40, v52, v40
	v_max_i32_e32 v11, v12, v15
	v_min_i32_e32 v12, v12, v15
	v_max_i32_e32 v15, v14, v13
	v_min_i32_e32 v13, v14, v13
	v_max_i32_e32 v14, v88, v3
	v_min_i32_e32 v3, v88, v3
	v_max_i32_e32 v88, v1, v0
	v_min_i32_e32 v0, v1, v0
	v_max_i32_e32 v1, v5, v6
	v_min_i32_e32 v5, v5, v6
	v_max_i32_e32 v6, v9, v2
	v_min_i32_e32 v2, v9, v2
	v_max_i32_e32 v9, v10, v4
	v_min_i32_e32 v4, v10, v4
	v_max_i32_e32 v10, v8, v7
	v_min_i32_e32 v7, v8, v7
	v_max_i32_e32 v33, v36, v30
	v_min_i32_e32 v30, v36, v30
	v_max_i32_e32 v36, v37, v26
	v_min_i32_e32 v26, v37, v26
	v_max_i32_e32 v37, v39, v25
	v_min_i32_e32 v25, v39, v25
	v_max_i32_e32 v39, v27, v31
	v_min_i32_e32 v27, v27, v31
	v_max_i32_e32 v31, v38, v29
	v_min_i32_e32 v29, v38, v29
	v_max_i32_e32 v38, v28, v34
	v_min_i32_e32 v28, v28, v34
	v_max_i32_e32 v34, v42, v32
	v_min_i32_e32 v32, v42, v32
	v_max_i32_e32 v42, v24, v35
	v_min_i32_e32 v24, v24, v35
	v_max_i32_e32 v63, v66, v60
	v_min_i32_e32 v60, v66, v60
	v_max_i32_e32 v66, v67, v56
	v_min_i32_e32 v56, v67, v56
	v_max_i32_e32 v67, v69, v55
	v_min_i32_e32 v55, v69, v55
	v_max_i32_e32 v69, v57, v61
	v_min_i32_e32 v57, v57, v61
	v_max_i32_e32 v61, v68, v59
	v_min_i32_e32 v59, v68, v59
	v_max_i32_e32 v68, v58, v64
	v_min_i32_e32 v58, v58, v64
	v_max_i32_e32 v64, v70, v62
	v_min_i32_e32 v62, v70, v62
	v_max_i32_e32 v70, v51, v65
	v_min_i32_e32 v51, v51, v65
	v_max_i32_e32 v52, v80, v21
	v_min_i32_e32 v21, v80, v21
	v_max_i32_e32 v80, v44, v17
	v_min_i32_e32 v17, v44, v17
	v_max_i32_e32 v44, v54, v18
	v_min_i32_e32 v18, v54, v18
	v_max_i32_e32 v54, v23, v22
	v_min_i32_e32 v22, v23, v22
	v_max_i32_e32 v23, v41, v20
	v_min_i32_e32 v20, v41, v20
	v_max_i32_e32 v41, v19, v53
	v_min_i32_e32 v19, v19, v53
	v_max_i32_e32 v53, v78, v40
	v_min_i32_e32 v40, v78, v40
	v_max_i32_e32 v78, v16, v79
	v_min_i32_e32 v16, v16, v79
	v_max_i32_e32 v8, v11, v5
	v_min_i32_e32 v5, v11, v5
	v_max_i32_e32 v11, v12, v1
	v_min_i32_e32 v1, v12, v1
	v_max_i32_e32 v12, v15, v2
	v_min_i32_e32 v2, v15, v2
	v_max_i32_e32 v15, v13, v6
	v_min_i32_e32 v6, v13, v6
	v_max_i32_e32 v13, v14, v4
	v_min_i32_e32 v4, v14, v4
	v_max_i32_e32 v14, v3, v9
	v_min_i32_e32 v3, v3, v9
	v_max_i32_e32 v9, v88, v7
	v_min_i32_e32 v7, v88, v7
	v_max_i32_e32 v88, v0, v10
	v_min_i32_e32 v0, v0, v10
	v_max_i32_e32 v35, v33, v31
	v_min_i32_e32 v31, v33, v31
	v_max_i32_e32 v33, v36, v38
	v_min_i32_e32 v36, v36, v38
	v_max_i32_e32 v38, v37, v34
	v_min_i32_e32 v34, v37, v34
	v_max_i32_e32 v37, v39, v42
	v_min_i32_e32 v39, v39, v42
	v_max_i32_e32 v42, v30, v29
	v_min_i32_e32 v29, v30, v29
	v_max_i32_e32 v30, v26, v28
	v_min_i32_e32 v26, v26, v28
	v_max_i32_e32 v28, v25, v32
	v_min_i32_e32 v25, v25, v32
	v_max_i32_e32 v32, v27, v24
	v_min_i32_e32 v24, v27, v24
	v_max_i32_e32 v65, v63, v61
	v_min_i32_e32 v61, v63, v61
	v_max_i32_e32 v63, v66, v68
	v_min_i32_e32 v66, v66, v68
	v_max_i32_e32 v68, v67, v64
	v_min_i32_e32 v64, v67, v64
	v_max_i32_e32 v67, v69, v70
	v_min_i32_e32 v69, v69, v70
	v_max_i32_e32 v70, v60, v59
	v_min_i32_e32 v59, v60, v59
	v_max_i32_e32 v60, v56, v58
	v_min_i32_e32 v56, v56, v58
	v_max_i32_e32 v58, v55, v62
	v_min_i32_e32 v55, v55, v62
	v_max_i32_e32 v62, v57, v51
	v_min_i32_e32 v51, v57, v51
	v_max_i32_e32 v79, v52, v23
	v_min_i32_e32 v23, v52, v23
	v_max_i32_e32 v52, v80, v41
	v_min_i32_e32 v41, v80, v41
	v_max_i32_e32 v80, v44, v53
	v_min_i32_e32 v44, v44, v53
	v_max_i32_e32 v53, v54, v78
	v_min_i32_e32 v54, v54, v78
	v_max_i32_e32 v78, v21, v20
	v_min_i32_e32 v20, v21, v20
	v_max_i32_e32 v21, v17, v19
	v_min_i32_e32 v17, v17, v19
	v_max_i32_e32 v19, v18, v40
	v_min_i32_e32 v18, v18, v40
	v_max_i32_e32 v40, v22, v16
	v_min_i32_e32 v16, v22, v16
	v_max_i32_e32 v10, v8, v13
	v_min_i32_e32 v8, v8, v13
	v_max_i32_e32 v13, v11, v14
	v_min_i32_e32 v11, v11, v14
	v_max_i32_e32 v14, v12, v9
	v_min_i32_e32 v9, v12, v9
	v_max_i32_e32 v12, v15, v88
	v_min_i32_e32 v15, v15, v88
	v_max_i32_e32 v88, v5, v4
	v_min_i32_e32 v4, v5, v4
	v_max_i32_e32 v5, v1, v3
	v_min_i32_e32 v1, v1, v3
	v_max_i32_e32 v3, v2, v7
	v_min_i32_e32 v2, v2, v7
	v_max_i32_e32 v7, v6, v0
	v_min_i32_e32 v0, v6, v0
	v_max_i32_e32 v27, v35, v38
	v_min_i32_e32 v35, v35, v38
	v_max_i32_e32 v38, v33, v37
	v_min_i32_e32 v33, v33, v37
	v_max_i32_e32 v37, v31, v34
	v_min_i32_e32 v31, v31, v34
	v_max_i32_e32 v34, v36, v39
	v_min_i32_e32 v36, v36, v39
	v_max_i32_e32 v39, v42, v28
	v_min_i32_e32 v28, v42, v28
	v_max_i32_e32 v42, v30, v32
	v_min_i32_e32 v30, v30, v32
	v_max_i32_e32 v32, v29, v25
	v_min_i32_e32 v25, v29, v25
	v_max_i32_e32 v29, v26, v24
	v_min_i32_e32 v24, v26, v24
	v_max_i32_e32 v57, v65, v68
	v_min_i32_e32 v65, v65, v68
	v_max_i32_e32 v68, v63, v67
	v_min_i32_e32 v63, v63, v67
	v_max_i32_e32 v67, v61, v64
	v_min_i32_e32 v61, v61, v64
	v_max_i32_e32 v64, v66, v69
	v_min_i32_e32 v66, v66, v69
	v_max_i32_e32 v69, v70, v58
	v_min_i32_e32 v58, v70, v58
	v_max_i32_e32 v70, v60, v62
	v_min_i32_e32 v60, v60, v62
	v_max_i32_e32 v62, v59, v55
	v_min_i32_e32 v55, v59, v55
	v_max_i32_e32 v59, v56, v51
	v_min_i32_e32 v51, v56, v51
	v_max_i32_e32 v22, v79, v80
	v_min_i32_e32 v79, v79, v80
	v_max_i32_e32 v80, v52, v53
	v_min_i32_e32 v52, v52, v53
	v_max_i32_e32 v53, v23, v44
	v_min_i32_e32 v23, v23, v44
	v_max_i32_e32 v44, v41, v54
	v_min_i32_e32 v41, v41, v54
	v_max_i32_e32 v54, v78, v19
	v_min_i32_e32 v19, v78, v19
	v_max_i32_e32 v78, v21, v40
	v_min_i32_e32 v21, v21, v40
	v_max_i32_e32 v40, v20, v18
	v_min_i32_e32 v18, v20, v18
	v_max_i32_e32 v20, v17, v16
	v_min_i32_e32 v16, v17, v16
	v_max_i32_e32 v6, v10, v14
	v_min_i32_e32 v10, v10, v14
	v_max_i32_e32 v14, v13, v12
	v_min_i32_e32 v12, v13, v12
	v_max_i32_e32 v13, v8, v9
	v_min_i32_e32 v8, v8, v9
	v_max_i32_e32 v9, v11, v15
	v_min_i32_e32 v11, v11, v15
	v_max_i32_e32 v15, v88, v3
	v_min_i32_e32 v3, v88, v3
	v_max_i32_e32 v88, v5, v7
	v_min_i32_e32 v5, v5, v7
	v_max_i32_e32 v7, v4, v2
	v_min_i32_e32 v2, v4, v2
	v_max_i32_e32 v4, v1, v0
	v_min_i32_e32 v0, v1, v0
	v_min_i32_e32 v26, v27, v38
	v_min_i32_e32 v43, v35, v33
	v_min_i32_e32 v45, v37, v34
	v_min_i32_e32 v46, v31, v36
	v_min_i32_e32 v47, v39, v42
	v_min_i32_e32 v48, v28, v30
	v_min_i32_e32 v49, v32, v29
	v_min_i32_e32 v50, v25, v24
	v_min_i32_e32 v56, v57, v68
	v_min_i32_e32 v71, v65, v63
	v_min_i32_e32 v72, v67, v64
	v_min_i32_e32 v73, v61, v66
	v_min_i32_e32 v74, v69, v70
	v_min_i32_e32 v75, v58, v60
	v_min_i32_e32 v76, v62, v59
	v_min_i32_e32 v77, v55, v51
	v_min_i32_e32 v17, v22, v80
	v_min_i32_e32 v81, v79, v52
	v_min_i32_e32 v82, v53, v44
	v_min_i32_e32 v83, v23, v41
	v_min_i32_e32 v84, v54, v78
	v_min_i32_e32 v85, v19, v21
	v_min_i32_e32 v86, v40, v20
	v_min_i32_e32 v87, v18, v16
	v_min_i32_e32 v1, v6, v14
	v_min_i32_e32 v89, v10, v12
	v_min_i32_e32 v90, v13, v9
	v_min_i32_e32 v91, v8, v11
	v_min_i32_e32 v92, v15, v88
	v_min_i32_e32 v93, v3, v5
	v_min_i32_e32 v94, v7, v4
	v_min_i32_e32 v95, v2, v0
	v_max3_i32 v27, v27, v38, v77
	v_max3_i32 v26, v26, v55, v51
	v_max3_i32 v33, v35, v33, v76
	v_max3_i32 v35, v43, v62, v59
	v_max3_i32 v34, v37, v34, v75
	v_max3_i32 v37, v45, v58, v60
	v_max3_i32 v31, v31, v36, v74
	v_max3_i32 v36, v46, v69, v70
	v_max3_i32 v38, v39, v42, v73
	v_max3_i32 v39, v47, v61, v66
	v_max3_i32 v28, v28, v30, v72
	v_max3_i32 v30, v48, v67, v64
	v_max3_i32 v29, v32, v29, v71
	v_max3_i32 v32, v49, v65, v63
	v_max3_i32 v24, v25, v24, v56
	v_max3_i32 v25, v50, v57, v68
	v_max3_i32 v22, v22, v80, v95
	v_max3_i32 v0, v17, v2, v0
	v_max3_i32 v2, v79, v52, v94
	v_max3_i32 v4, v81, v7, v4
	v_max3_i32 v7, v53, v44, v93
	v_max3_i32 v3, v82, v3, v5
	v_max3_i32 v5, v23, v41, v92
	v_max3_i32 v15, v83, v15, v88
	v_max3_i32 v17, v54, v78, v91
	v_max3_i32 v8, v84, v8, v11
	v_max3_i32 v11, v19, v21, v90
	v_max3_i32 v9, v85, v13, v9
	v_max3_i32 v13, v40, v20, v89
	v_max3_i32 v10, v86, v10, v12
	v_max3_i32 v1, v18, v16, v1
	v_max3_i32 v6, v87, v6, v14
	v_max_i32_e32 v42, v27, v38
	v_min_i32_e32 v27, v27, v38
	v_max_i32_e32 v38, v26, v39
	v_min_i32_e32 v26, v26, v39
	v_max_i32_e32 v39, v33, v28
	v_min_i32_e32 v28, v33, v28
	v_max_i32_e32 v33, v35, v30
	v_min_i32_e32 v30, v35, v30
	v_max_i32_e32 v35, v34, v29
	v_min_i32_e32 v29, v34, v29
	v_max_i32_e32 v34, v37, v32
	v_min_i32_e32 v32, v37, v32
	v_max_i32_e32 v37, v31, v24
	v_min_i32_e32 v24, v31, v24
	v_max_i32_e32 v31, v36, v25
	v_min_i32_e32 v25, v36, v25
	v_max_i32_e32 v12, v22, v17
	v_min_i32_e32 v14, v22, v17
	v_max_i32_e32 v16, v0, v8
	v_min_i32_e32 v0, v0, v8
	v_max_i32_e32 v8, v2, v11
	v_min_i32_e32 v2, v2, v11
	v_max_i32_e32 v11, v4, v9
	v_min_i32_e32 v4, v4, v9
	v_max_i32_e32 v9, v7, v13
	v_min_i32_e32 v7, v7, v13
	v_max_i32_e32 v13, v3, v10
	v_min_i32_e32 v3, v3, v10
	v_max_i32_e32 v10, v5, v1
	v_min_i32_e32 v1, v5, v1
	v_max_i32_e32 v5, v15, v6
	v_min_i32_e32 v6, v15, v6
	v_max_i32_e32 v36, v42, v35
	v_min_i32_e32 v35, v42, v35
	v_max_i32_e32 v42, v38, v34
	v_min_i32_e32 v34, v38, v34
	v_max_i32_e32 v38, v39, v37
	v_min_i32_e32 v37, v39, v37
	v_max_i32_e32 v39, v33, v31
	v_min_i32_e32 v31, v33, v31
	v_max_i32_e32 v33, v27, v29
	v_min_i32_e32 v27, v27, v29
	v_max_i32_e32 v29, v26, v32
	v_min_i32_e32 v26, v26, v32
	v_max_i32_e32 v32, v28, v24
	v_min_i32_e32 v24, v28, v24
	v_max_i32_e32 v28, v30, v25
	v_min_i32_e32 v25, v30, v25
	v_max_i32_e32 v15, v12, v9
	v_min_i32_e32 v9, v12, v9
	v_max_i32_e32 v12, v16, v13
	v_min_i32_e32 v13, v16, v13
	v_max_i32_e32 v16, v8, v10
	v_min_i32_e32 v8, v8, v10
	v_max_i32_e32 v10, v11, v5
	v_min_i32_e32 v5, v11, v5
	v_max_i32_e32 v11, v14, v7
	v_min_i32_e32 v7, v14, v7
	v_max_i32_e32 v14, v0, v3
	v_min_i32_e32 v0, v0, v3
	v_max_i32_e32 v3, v2, v1
	v_min_i32_e32 v1, v2, v1
	v_max_i32_e32 v2, v4, v6
	v_min_i32_e32 v4, v4, v6
	v_max_i32_e32 v30, v36, v38
	v_min_i32_e32 v36, v36, v38
	v_max_i32_e32 v38, v42, v39
	v_min_i32_e32 v39, v42, v39
	v_max_i32_e32 v42, v35, v37
	v_min_i32_e32 v35, v35, v37
	v_max_i32_e32 v37, v34, v31
	v_min_i32_e32 v31, v34, v31
	v_max_i32_e32 v34, v33, v32
	v_min_i32_e32 v32, v33, v32
	v_max_i32_e32 v33, v29, v28
	v_min_i32_e32 v28, v29, v28
	v_max_i32_e32 v29, v27, v24
	v_min_i32_e32 v24, v27, v24
	v_max_i32_e32 v27, v26, v25
	v_min_i32_e32 v25, v26, v25
	v_max_i32_e32 v6, v15, v16
	v_min_i32_e32 v15, v15, v16
	v_max_i32_e32 v16, v12, v10
	v_min_i32_e32 v10, v12, v10
	v_max_i32_e32 v12, v9, v8
	v_min_i32_e32 v8, v9, v8
	v_max_i32_e32 v9, v13, v5
	v_min_i32_e32 v5, v13, v5
	v_max_i32_e32 v13, v11, v3
	v_min_i32_e32 v3, v11, v3
	v_max_i32_e32 v11, v14, v2
	v_min_i32_e32 v2, v14, v2
	v_max_i32_e32 v14, v7, v1
	v_min_i32_e32 v1, v7, v1
	v_max_i32_e32 v7, v0, v4
	v_min_i32_e32 v0, v0, v4
	v_min_i32_e32 v26, v30, v38
	v_min_i32_e32 v43, v36, v39
	v_min_i32_e32 v45, v42, v37
	v_min_i32_e32 v46, v35, v31
	v_min_i32_e32 v47, v34, v33
	v_min_i32_e32 v48, v32, v28
	v_min_i32_e32 v49, v29, v27
	v_min_i32_e32 v50, v24, v25
	v_min_i32_e32 v4, v6, v16
	v_min_i32_e32 v17, v15, v10
	v_min_i32_e32 v18, v12, v9
	v_min_i32_e32 v19, v8, v5
	v_min_i32_e32 v20, v13, v11
	v_min_i32_e32 v21, v3, v2
	v_min_i32_e32 v22, v14, v7
	v_min_i32_e32 v23, v1, v0
	v_max3_i32 v23, v30, v38, v23
	v_max3_i32 v0, v26, v1, v0
	v_max3_i32 v1, v36, v39, v22
	v_max3_i32 v7, v43, v14, v7
	v_max3_i32 v14, v42, v37, v21
	v_max3_i32 v2, v45, v3, v2
	v_max3_i32 v3, v35, v31, v20
	v_max3_i32 v11, v46, v13, v11
	v_max3_i32 v13, v34, v33, v19
	v_max3_i32 v5, v47, v8, v5
	v_max3_i32 v8, v32, v28, v18
	v_max3_i32 v9, v48, v12, v9
	v_max3_i32 v12, v29, v27, v17
	v_max3_i32 v10, v49, v15, v10
	v_max3_i32 v4, v24, v25, v4
	v_max3_i32 v6, v50, v6, v16
	v_max_i32_e32 v15, v23, v13
	v_min_i32_e32 v13, v23, v13
	v_max_i32_e32 v16, v0, v5
	v_min_i32_e32 v0, v0, v5
	v_max_i32_e32 v5, v1, v8
	v_min_i32_e32 v1, v1, v8
	v_max_i32_e32 v8, v7, v9
	v_min_i32_e32 v7, v7, v9
	v_max_i32_e32 v9, v14, v12
	v_min_i32_e32 v12, v14, v12
	v_max_i32_e32 v14, v2, v10
	v_min_i32_e32 v2, v2, v10
	v_max_i32_e32 v10, v3, v4
	v_min_i32_e32 v3, v3, v4
	v_max_i32_e32 v4, v11, v6
	v_min_i32_e32 v6, v11, v6
	v_max_i32_e32 v11, v15, v9
	v_min_i32_e32 v9, v15, v9
	v_max_i32_e32 v15, v16, v14
	v_min_i32_e32 v14, v16, v14
	v_max_i32_e32 v16, v5, v10
	v_min_i32_e32 v5, v5, v10
	v_max_i32_e32 v10, v8, v4
	v_min_i32_e32 v4, v8, v4
	v_max_i32_e32 v8, v13, v12
	v_min_i32_e32 v12, v13, v12
	v_max_i32_e32 v13, v0, v2
	v_min_i32_e32 v0, v0, v2
	v_max_i32_e32 v2, v1, v3
	v_min_i32_e32 v1, v1, v3
	v_max_i32_e32 v3, v7, v6
	v_min_i32_e32 v6, v7, v6
	v_max_i32_e32 v7, v11, v16
	v_min_i32_e32 v11, v11, v16
	v_max_i32_e32 v16, v15, v10
	v_min_i32_e32 v10, v15, v10
	v_max_i32_e32 v15, v9, v5
	v_min_i32_e32 v5, v9, v5
	v_max_i32_e32 v9, v14, v4
	v_min_i32_e32 v4, v14, v4
	v_max_i32_e32 v14, v8, v2
	v_min_i32_e32 v2, v8, v2
	v_max_i32_e32 v8, v13, v3
	v_min_i32_e32 v3, v13, v3
	v_max_i32_e32 v13, v12, v1
	v_min_i32_e32 v1, v12, v1
	v_max_i32_e32 v12, v0, v6
	v_min_i32_e32 v0, v0, v6
	v_max_i32_e32 v6, v7, v16
	v_min_i32_e32 v7, v7, v16
	v_max_i32_e32 v16, v11, v10
	v_min_i32_e32 v10, v11, v10
	v_max_i32_e32 v11, v15, v9
	v_min_i32_e32 v9, v15, v9
	v_max_i32_e32 v15, v5, v4
	v_min_i32_e32 v4, v5, v4
	v_max_i32_e32 v5, v14, v8
	v_min_i32_e32 v8, v14, v8
	v_max_i32_e32 v14, v2, v3
	v_min_i32_e32 v2, v2, v3
	v_max_i32_e32 v3, v13, v12
	v_min_i32_e32 v13, v13, v12
	v_and_b32_e32 v12, 64, v188
	v_max_i32_e32 v17, v1, v0
	v_min_i32_e32 v0, v1, v0
	v_xor_b32_e32 v1, 32, v188
	v_add_u32_e32 v12, 64, v12
	v_cmp_lt_i32_e32 vcc, v1, v12
	s_barrier
	s_nop 0
	v_cndmask_b32_e32 v1, v188, v1, vcc
	v_lshlrev_b32_e32 v12, 2, v1
	ds_bpermute_b32 v1, v12, v6
	ds_bpermute_b32 v18, v12, v7
	ds_bpermute_b32 v19, v12, v16
	ds_bpermute_b32 v20, v12, v10
	ds_bpermute_b32 v21, v12, v11
	ds_bpermute_b32 v22, v12, v9
	ds_bpermute_b32 v23, v12, v15
	ds_bpermute_b32 v24, v12, v4
	ds_bpermute_b32 v25, v12, v5
	ds_bpermute_b32 v26, v12, v8
	ds_bpermute_b32 v27, v12, v14
	ds_bpermute_b32 v28, v12, v0
	ds_bpermute_b32 v29, v12, v17
	ds_bpermute_b32 v30, v12, v13
	ds_bpermute_b32 v31, v12, v3
	ds_bpermute_b32 v32, v12, v2
	s_waitcnt lgkmcnt(4)
	v_max_i32_e32 v6, v6, v28
	s_waitcnt lgkmcnt(3)
	v_max_i32_e32 v7, v7, v29
	s_waitcnt lgkmcnt(2)
	v_max_i32_e32 v16, v16, v30
	s_waitcnt lgkmcnt(1)
	v_max_i32_e32 v10, v10, v31
	s_waitcnt lgkmcnt(0)
	v_max_i32_e32 v11, v11, v32
	v_max_i32_e32 v9, v9, v27
	v_max_i32_e32 v15, v15, v26
	v_max_i32_e32 v4, v4, v25
	v_max_i32_e32 v5, v5, v24
	v_max_i32_e32 v8, v8, v23
	v_max_i32_e32 v14, v14, v22
	v_max_i32_e32 v2, v2, v21
	v_max_i32_e32 v3, v3, v20
	v_max_i32_e32 v13, v13, v19
	v_max_i32_e32 v17, v17, v18
	v_max_i32_e32 v0, v0, v1
	v_max_i32_e32 v1, v6, v5
	v_min_i32_e32 v5, v6, v5
	v_max_i32_e32 v6, v7, v8
	v_min_i32_e32 v7, v7, v8
	v_max_i32_e32 v8, v16, v14
	v_min_i32_e32 v14, v16, v14
	v_max_i32_e32 v16, v10, v2
	v_min_i32_e32 v2, v10, v2
	v_max_i32_e32 v10, v11, v3
	v_min_i32_e32 v3, v11, v3
	v_max_i32_e32 v11, v9, v13
	v_min_i32_e32 v9, v9, v13
	v_max_i32_e32 v13, v15, v17
	v_min_i32_e32 v15, v15, v17
	v_max_i32_e32 v17, v4, v0
	v_min_i32_e32 v0, v4, v0
	v_max_i32_e32 v4, v1, v10
	v_min_i32_e32 v1, v1, v10
	v_max_i32_e32 v10, v6, v11
	v_min_i32_e32 v6, v6, v11
	v_max_i32_e32 v11, v8, v13
	v_min_i32_e32 v8, v8, v13
	v_max_i32_e32 v13, v16, v17
	v_min_i32_e32 v16, v16, v17
	v_max_i32_e32 v17, v5, v3
	v_min_i32_e32 v3, v5, v3
	v_max_i32_e32 v5, v7, v9
	v_min_i32_e32 v7, v7, v9
	v_max_i32_e32 v9, v14, v15
	v_min_i32_e32 v14, v14, v15
	v_max_i32_e32 v15, v2, v0
	v_min_i32_e32 v0, v2, v0
	v_max_i32_e32 v2, v4, v11
	v_min_i32_e32 v4, v4, v11
	v_max_i32_e32 v11, v10, v13
	v_min_i32_e32 v10, v10, v13
	v_max_i32_e32 v13, v1, v8
	v_min_i32_e32 v1, v1, v8
	v_max_i32_e32 v8, v6, v16
	v_min_i32_e32 v6, v6, v16
	v_max_i32_e32 v16, v17, v9
	v_min_i32_e32 v9, v17, v9
	v_max_i32_e32 v17, v5, v15
	v_min_i32_e32 v5, v5, v15
	v_max_i32_e32 v15, v3, v14
	v_min_i32_e32 v3, v3, v14
	v_max_i32_e32 v14, v7, v0
	v_min_i32_e32 v0, v7, v0
	v_max_i32_e32 v7, v2, v11
	v_min_i32_e32 v2, v2, v11
	v_max_i32_e32 v25, v3, v0
	v_min_i32_e32 v26, v3, v0
	v_ashrrev_i32_e32 v0, 31, v7
	v_max_i32_e32 v11, v4, v10
	v_bitop3_b32 v20, v0, v7, s11 bitop3:0x6c
	v_ashrrev_i32_e32 v0, 31, v2
	v_min_i32_e32 v4, v4, v10
	v_bitop3_b32 v19, v0, v2, s11 bitop3:0x6c
	v_ashrrev_i32_e32 v0, 31, v11
	v_max_i32_e32 v10, v13, v8
	v_bitop3_b32 v18, v0, v11, s11 bitop3:0x6c
	v_ashrrev_i32_e32 v0, 31, v4
	v_min_i32_e32 v8, v13, v8
	v_max_i32_e32 v13, v1, v6
	v_min_i32_e32 v1, v1, v6
	v_max_i32_e32 v6, v16, v17
	v_min_i32_e32 v21, v16, v17
	v_bitop3_b32 v17, v0, v4, s11 bitop3:0x6c
	v_ashrrev_i32_e32 v0, 31, v10
	v_bitop3_b32 v16, v0, v10, s11 bitop3:0x6c
	v_ashrrev_i32_e32 v0, 31, v8
	v_max_i32_e32 v23, v15, v14
	v_min_i32_e32 v24, v15, v14
	v_bitop3_b32 v15, v0, v8, s11 bitop3:0x6c
	v_ashrrev_i32_e32 v0, 31, v13
	v_bitop3_b32 v14, v0, v13, s11 bitop3:0x6c
	v_ashrrev_i32_e32 v0, 31, v1
	v_bitop3_b32 v13, v0, v1, s11 bitop3:0x6c
	v_ashrrev_i32_e32 v0, 31, v6
	v_ashrrev_i32_e32 v1, 31, v21
	v_max_i32_e32 v22, v9, v5
	v_min_i32_e32 v9, v9, v5
	v_and_b32_e32 v0, 0x7fffffff, v0
	v_and_b32_e32 v2, 0x7fffffff, v1
	v_xor_b32_e32 v1, v0, v6
	v_xor_b32_e32 v0, v2, v21
	v_ashrrev_i32_e32 v2, 31, v22
	v_ashrrev_i32_e32 v3, 31, v9
	v_and_b32_e32 v2, 0x7fffffff, v2
	v_and_b32_e32 v3, 0x7fffffff, v3
	v_xor_b32_e32 v5, v2, v22
	v_xor_b32_e32 v4, v3, v9
	v_ashrrev_i32_e32 v2, 31, v23
	v_ashrrev_i32_e32 v3, 31, v24
	v_and_b32_e32 v2, 0x7fffffff, v2
	v_and_b32_e32 v6, 0x7fffffff, v3
	v_xor_b32_e32 v3, v2, v23
	v_xor_b32_e32 v2, v6, v24
	v_ashrrev_i32_e32 v6, 31, v25
	v_bitop3_b32 v11, v6, v25, s11 bitop3:0x6c
	v_ashrrev_i32_e32 v6, 31, v26
	v_bitop3_b32 v10, v6, v26, s11 bitop3:0x6c
	s_and_b64 vcc, exec, s[56:57]
	s_cbranch_vccnz .LBB0_1001
	v_mov_b32_e32 v221, v20
	v_mov_b32_e32 v222, v19
	v_mov_b32_e32 v223, v18
	v_mov_b32_e32 v224, v17
	v_mov_b32_e32 v225, v16
	v_mov_b32_e32 v226, v15
	v_mov_b32_e32 v227, v14
	v_mov_b32_e32 v228, v13
	v_mov_b32_e32 v229, v11
	v_mov_b32_e32 v230, v10
	v_mov_b64_e32 v[154:155], v[2:3]
	v_mov_b64_e32 v[156:157], v[4:5]
	v_mov_b64_e32 v[158:159], v[0:1]
	s_branch .LBB0_1003
